# first 4 MFMAs of each merged K-loop block issued before the block's barrier, on top of the ss LDS-DMA + hand-scheduled mLSTM version
# speedup vs baseline: 1.0106x; 1.0106x over previous
.Lrs_i2_pre:
	s_add_u32 s1, s28, 0xfffc0080
	s_addc_u32 s22, s29, -1
	s_add_i32 s23, 0, 0x10000
	v_add_u32_e32 v142, s23, v201
	ds_read_b128 v[130:133], v142
	ds_read_b128 v[134:137], v142 offset:1024
	ds_read_b128 v[138:141], v142 offset:2048
	ds_read_b128 v[142:145], v142 offset:3072
	s_cmp_eq_u32 s60, 12
	s_cselect_b32 s43, s27, s22
	s_cselect_b32 s42, s56, s1
	s_cselect_b32 s31, s7, s59
	s_cselect_b32 s30, s57, s58
	v_lshl_add_u64 v[176:177], s[28:29], 0, v[178:179]
	s_add_i32 m0, s46, 0xc000
	ds_read_b128 v[146:149], v205
	ds_read_b128 v[150:153], v205 offset:1024
	ds_read_b128 v[182:185], v205 offset:2048
	ds_read_b128 v[186:189], v205 offset:3072
	ds_read_b128 v[190:193], v205 offset:4096
	ds_read_b128 v[194:197], v205 offset:5120
	ds_read_b128 v[206:209], v205 offset:6144
	ds_read_b128 v[216:219], v205 offset:7168
	global_load_lds_dwordx4 v[176:177], off
	v_lshl_add_u64 v[176:177], s[28:29], 0, v[180:181]
	s_add_i32 m0, s46, 0xe000
	s_nop 0
	global_load_lds_dwordx4 v[176:177], off
	s_add_i32 s1, 0, 0x14000
	v_add_u32_e32 v168, s1, v201
	ds_read_b128 v[230:233], v168
	ds_read_b128 v[234:237], v168 offset:1024
	ds_read_b128 v[238:241], v168 offset:2048
	ds_read_b128 v[242:245], v168 offset:3072
	s_waitcnt vmcnt(8)
	s_waitcnt lgkmcnt(0)
	v_mfma_f32_16x16x32_bf16 v[126:129], v[130:133], v[146:149], 0
	v_mfma_f32_16x16x32_bf16 v[118:121], v[138:141], v[146:149], 0
	v_mfma_f32_16x16x32_bf16 v[110:113], v[130:133], v[182:185], 0
	v_mfma_f32_16x16x32_bf16 v[102:105], v[138:141], v[182:185], 0
	s_barrier
	s_setprio 1
	v_mfma_f32_16x16x32_bf16 v[94:97], v[130:133], v[190:193], 0
	v_mfma_f32_16x16x32_bf16 v[86:89], v[138:141], v[190:193], 0
	v_mfma_f32_16x16x32_bf16 v[78:81], v[130:133], v[206:209], 0
	v_mfma_f32_16x16x32_bf16 v[70:73], v[138:141], v[206:209], 0
	v_mfma_f32_16x16x32_bf16 v[126:129], v[134:137], v[150:153], v[126:129]
	v_mfma_f32_16x16x32_bf16 v[118:121], v[142:145], v[150:153], v[118:121]
	v_mfma_f32_16x16x32_bf16 v[110:113], v[134:137], v[186:189], v[110:113]
	v_mfma_f32_16x16x32_bf16 v[102:105], v[142:145], v[186:189], v[102:105]
	v_mfma_f32_16x16x32_bf16 v[94:97], v[134:137], v[194:197], v[94:97]
	v_mfma_f32_16x16x32_bf16 v[86:89], v[142:145], v[194:197], v[86:89]
	v_mfma_f32_16x16x32_bf16 v[78:81], v[134:137], v[216:219], v[78:81]
	v_mfma_f32_16x16x32_bf16 v[70:73], v[142:145], v[216:219], v[70:73]
	v_mfma_f32_16x16x32_bf16 v[122:125], v[230:233], v[146:149], 0
	v_mfma_f32_16x16x32_bf16 v[114:117], v[238:241], v[146:149], 0
	v_mfma_f32_16x16x32_bf16 v[106:109], v[230:233], v[182:185], 0
	v_mfma_f32_16x16x32_bf16 v[98:101], v[238:241], v[182:185], 0
	v_mfma_f32_16x16x32_bf16 v[90:93], v[230:233], v[190:193], 0
	v_mfma_f32_16x16x32_bf16 v[82:85], v[238:241], v[190:193], 0
	v_mfma_f32_16x16x32_bf16 v[74:77], v[230:233], v[206:209], 0
	v_mfma_f32_16x16x32_bf16 v[66:69], v[238:241], v[206:209], 0
	v_mfma_f32_16x16x32_bf16 v[122:125], v[234:237], v[150:153], v[122:125]
	v_mfma_f32_16x16x32_bf16 v[114:117], v[242:245], v[150:153], v[114:117]
	v_mfma_f32_16x16x32_bf16 v[106:109], v[234:237], v[186:189], v[106:109]
	v_mfma_f32_16x16x32_bf16 v[98:101], v[242:245], v[186:189], v[98:101]
	v_mfma_f32_16x16x32_bf16 v[90:93], v[234:237], v[194:197], v[90:93]
	v_mfma_f32_16x16x32_bf16 v[82:85], v[242:245], v[194:197], v[82:85]
	v_mfma_f32_16x16x32_bf16 v[74:77], v[234:237], v[216:219], v[74:77]
	v_mfma_f32_16x16x32_bf16 v[66:69], v[242:245], v[216:219], v[66:69]
	s_setprio 0
	s_barrier
	ds_read_b128 v[146:149], v205 offset:16384
	ds_read_b128 v[150:153], v205 offset:17408
	ds_read_b128 v[182:185], v205 offset:18432
	ds_read_b128 v[186:189], v205 offset:19456
	ds_read_b128 v[190:193], v205 offset:20480
	ds_read_b128 v[194:197], v205 offset:21504
	ds_read_b128 v[206:209], v205 offset:22528
	ds_read_b128 v[216:219], v205 offset:23552
	s_cbranch_vccz .Lss_i2
	v_lshlrev_b32_e32 v176, 4, v167
	s_lshl_b32 m0, s46, 1
	v_add_u32_e32 v176, s46, v176
	s_add_i32 m0, m0, 0x20000
	s_mov_b64 vcc, 0
	global_load_lds_dwordx4 v176, s[98:99]
	global_load_lds_dwordx4 v176, s[98:99] offset:1024
	s_add_i32 s22, s23, s17
	v_lshl_add_u64 v[176:177], s[30:31], 0, v[0:1]
	s_mov_b32 m0, s22
	s_nop 0
	global_load_lds_dwordx4 v[176:177], off
	v_lshl_add_u64 v[202:203], s[30:31], 0, v[154:155]
	s_add_i32 m0, s22, 0x2000
	s_nop 0
	global_load_lds_dwordx4 v[202:203], off
	s_mov_b32 m0, s46
	v_lshl_add_u64 v[220:221], s[42:43], 0, v[158:159]
	global_load_lds_dwordx4 v[220:221], off
	v_lshl_add_u64 v[246:247], s[42:43], 0, v[156:157]
	s_mov_b32 m0, s47
	s_nop 0
	global_load_lds_dwordx4 v[246:247], off
	s_add_u32 s22, s30, 0x40000
	s_addc_u32 s23, s31, 0
	s_add_i32 s1, s1, s17
	s_mov_b32 m0, s1
	s_nop 0
	global_load_lds_dwordx4 v0, s[22:23]
	s_add_i32 m0, s1, 0x2000
	s_nop 0
	global_load_lds_dwordx4 v154, s[22:23]
	s_waitcnt vmcnt(8)
	s_waitcnt lgkmcnt(0)
	v_mfma_f32_16x16x32_bf16 v[62:65], v[130:133], v[146:149], 0
	v_mfma_f32_16x16x32_bf16 v[54:57], v[138:141], v[146:149], 0
	v_mfma_f32_16x16x32_bf16 v[46:49], v[130:133], v[182:185], 0
	v_mfma_f32_16x16x32_bf16 v[38:41], v[138:141], v[182:185], 0
	s_barrier
	s_setprio 1
	v_mfma_f32_16x16x32_bf16 v[30:33], v[130:133], v[190:193], 0
	v_mfma_f32_16x16x32_bf16 v[22:25], v[138:141], v[190:193], 0
	v_mfma_f32_16x16x32_bf16 v[14:17], v[130:133], v[206:209], 0
	v_mfma_f32_16x16x32_bf16 v[6:9], v[138:141], v[206:209], 0
	v_mfma_f32_16x16x32_bf16 v[62:65], v[134:137], v[150:153], v[62:65]
	v_mfma_f32_16x16x32_bf16 v[54:57], v[142:145], v[150:153], v[54:57]
	v_mfma_f32_16x16x32_bf16 v[46:49], v[134:137], v[186:189], v[46:49]
	v_mfma_f32_16x16x32_bf16 v[38:41], v[142:145], v[186:189], v[38:41]
	v_mfma_f32_16x16x32_bf16 v[30:33], v[134:137], v[194:197], v[30:33]
	v_mfma_f32_16x16x32_bf16 v[22:25], v[142:145], v[194:197], v[22:25]
	v_mfma_f32_16x16x32_bf16 v[14:17], v[134:137], v[216:219], v[14:17]
	v_mfma_f32_16x16x32_bf16 v[6:9], v[142:145], v[216:219], v[6:9]
	v_mfma_f32_16x16x32_bf16 v[58:61], v[230:233], v[146:149], 0
	v_mfma_f32_16x16x32_bf16 v[50:53], v[238:241], v[146:149], 0
	v_mfma_f32_16x16x32_bf16 v[42:45], v[230:233], v[182:185], 0
	v_mfma_f32_16x16x32_bf16 v[34:37], v[238:241], v[182:185], 0
	v_mfma_f32_16x16x32_bf16 v[26:29], v[230:233], v[190:193], 0
	v_mfma_f32_16x16x32_bf16 v[18:21], v[238:241], v[190:193], 0
	v_mfma_f32_16x16x32_bf16 v[10:13], v[230:233], v[206:209], 0
	v_mfma_f32_16x16x32_bf16 v[2:5], v[238:241], v[206:209], 0
	v_mfma_f32_16x16x32_bf16 v[58:61], v[234:237], v[150:153], v[58:61]
	v_mfma_f32_16x16x32_bf16 v[50:53], v[242:245], v[150:153], v[50:53]
	v_mfma_f32_16x16x32_bf16 v[42:45], v[234:237], v[186:189], v[42:45]
	v_mfma_f32_16x16x32_bf16 v[34:37], v[242:245], v[186:189], v[34:37]
	v_mfma_f32_16x16x32_bf16 v[26:29], v[234:237], v[194:197], v[26:29]
	v_mfma_f32_16x16x32_bf16 v[18:21], v[242:245], v[194:197], v[18:21]
	v_mfma_f32_16x16x32_bf16 v[10:13], v[234:237], v[216:219], v[10:13]
	v_mfma_f32_16x16x32_bf16 v[2:5], v[242:245], v[216:219], v[2:5]
	s_setprio 0
	s_barrier
	s_add_i32 s1, 0, 0x18000
	v_add_u32_e32 v142, s1, v201
	ds_read_b128 v[130:133], v142
	ds_read_b128 v[134:137], v142 offset:1024
	ds_read_b128 v[138:141], v142 offset:2048
	ds_read_b128 v[142:145], v142 offset:3072
	s_add_u32 s22, s42, 0x40000
	s_addc_u32 s23, s43, 0
	s_mov_b32 m0, s48
	v_lshl_add_u64 v[230:231], s[22:23], 0, v[158:159]
	ds_read_b128 v[146:149], v205 offset:32768
	ds_read_b128 v[150:153], v205 offset:33792
	ds_read_b128 v[182:185], v205 offset:34816
	ds_read_b128 v[186:189], v205 offset:35840
	ds_read_b128 v[190:193], v205 offset:36864
	ds_read_b128 v[194:197], v205 offset:37888
	ds_read_b128 v[206:209], v205 offset:38912
	ds_read_b128 v[216:219], v205 offset:39936
	global_load_lds_dwordx4 v[230:231], off
	v_lshl_add_u64 v[230:231], s[22:23], 0, v[156:157]
	s_mov_b32 m0, s49
	s_nop 0
	global_load_lds_dwordx4 v[230:231], off
	s_add_i32 s33, 0, 0x1c000
	v_add_u32_e32 v168, s33, v201
	ds_read_b128 v[230:233], v168
	ds_read_b128 v[234:237], v168 offset:1024
	ds_read_b128 v[238:241], v168 offset:2048
	ds_read_b128 v[242:245], v168 offset:3072
	s_waitcnt vmcnt(8)
	s_waitcnt lgkmcnt(0)
	v_mfma_f32_16x16x32_bf16 v[126:129], v[130:133], v[146:149], v[126:129]
	v_mfma_f32_16x16x32_bf16 v[118:121], v[138:141], v[146:149], v[118:121]
	v_mfma_f32_16x16x32_bf16 v[110:113], v[130:133], v[182:185], v[110:113]
	v_mfma_f32_16x16x32_bf16 v[102:105], v[138:141], v[182:185], v[102:105]
	s_barrier
	s_setprio 1
	v_mfma_f32_16x16x32_bf16 v[94:97], v[130:133], v[190:193], v[94:97]
	v_mfma_f32_16x16x32_bf16 v[86:89], v[138:141], v[190:193], v[86:89]
	v_mfma_f32_16x16x32_bf16 v[78:81], v[130:133], v[206:209], v[78:81]
	v_mfma_f32_16x16x32_bf16 v[70:73], v[138:141], v[206:209], v[70:73]
	v_mfma_f32_16x16x32_bf16 v[126:129], v[134:137], v[150:153], v[126:129]
	v_mfma_f32_16x16x32_bf16 v[118:121], v[142:145], v[150:153], v[118:121]
	v_mfma_f32_16x16x32_bf16 v[110:113], v[134:137], v[186:189], v[110:113]
	v_mfma_f32_16x16x32_bf16 v[102:105], v[142:145], v[186:189], v[102:105]
	v_mfma_f32_16x16x32_bf16 v[94:97], v[134:137], v[194:197], v[94:97]
	v_mfma_f32_16x16x32_bf16 v[86:89], v[142:145], v[194:197], v[86:89]
	v_mfma_f32_16x16x32_bf16 v[78:81], v[134:137], v[216:219], v[78:81]
	v_mfma_f32_16x16x32_bf16 v[70:73], v[142:145], v[216:219], v[70:73]
	v_mfma_f32_16x16x32_bf16 v[122:125], v[230:233], v[146:149], v[122:125]
	v_mfma_f32_16x16x32_bf16 v[114:117], v[238:241], v[146:149], v[114:117]
	v_mfma_f32_16x16x32_bf16 v[106:109], v[230:233], v[182:185], v[106:109]
	v_mfma_f32_16x16x32_bf16 v[98:101], v[238:241], v[182:185], v[98:101]
	v_mfma_f32_16x16x32_bf16 v[90:93], v[230:233], v[190:193], v[90:93]
	v_mfma_f32_16x16x32_bf16 v[82:85], v[238:241], v[190:193], v[82:85]
	v_mfma_f32_16x16x32_bf16 v[74:77], v[230:233], v[206:209], v[74:77]
	v_mfma_f32_16x16x32_bf16 v[66:69], v[238:241], v[206:209], v[66:69]
	v_mfma_f32_16x16x32_bf16 v[122:125], v[234:237], v[150:153], v[122:125]
	v_mfma_f32_16x16x32_bf16 v[114:117], v[242:245], v[150:153], v[114:117]
	v_mfma_f32_16x16x32_bf16 v[106:109], v[234:237], v[186:189], v[106:109]
	v_mfma_f32_16x16x32_bf16 v[98:101], v[242:245], v[186:189], v[98:101]
	v_mfma_f32_16x16x32_bf16 v[90:93], v[234:237], v[194:197], v[90:93]
	v_mfma_f32_16x16x32_bf16 v[82:85], v[242:245], v[194:197], v[82:85]
	v_mfma_f32_16x16x32_bf16 v[74:77], v[234:237], v[216:219], v[74:77]
	v_mfma_f32_16x16x32_bf16 v[66:69], v[242:245], v[216:219], v[66:69]
	s_setprio 0
	s_barrier
	ds_read_b128 v[146:149], v205 offset:49152
	ds_read_b128 v[150:153], v205 offset:50176
	ds_read_b128 v[182:185], v205 offset:51200
	ds_read_b128 v[186:189], v205 offset:52224
	ds_read_b128 v[190:193], v205 offset:53248
	ds_read_b128 v[194:197], v205 offset:54272
	ds_read_b128 v[206:209], v205 offset:55296
	ds_read_b128 v[216:219], v205 offset:56320
	s_add_i32 s1, s1, s17
	v_lshl_add_u64 v[176:177], v[176:177], 0, s[12:13]
	s_mov_b32 m0, s1
	s_nop 0
	global_load_lds_dwordx4 v[176:177], off
	v_lshl_add_u64 v[176:177], v[202:203], 0, s[12:13]
	s_add_i32 m0, s1, 0x2000
	s_nop 0
	global_load_lds_dwordx4 v[176:177], off
	s_mov_b32 m0, s20
	v_lshl_add_u64 v[176:177], v[220:221], 0, s[12:13]
	global_load_lds_dwordx4 v[176:177], off
	v_lshl_add_u64 v[176:177], v[246:247], 0, s[12:13]
	s_mov_b32 m0, s21
	s_nop 0
	global_load_lds_dwordx4 v[176:177], off
	s_add_u32 s22, s30, 0x40080
	s_addc_u32 s23, s31, 0
	s_add_i32 s1, s33, s17
	s_mov_b32 m0, s1
	s_nop 0
	global_load_lds_dwordx4 v0, s[22:23]
	s_add_i32 m0, s1, 0x2000
	s_nop 0
	global_load_lds_dwordx4 v154, s[22:23]
	s_waitcnt vmcnt(8)
	s_waitcnt lgkmcnt(0)
	v_mfma_f32_16x16x32_bf16 v[62:65], v[130:133], v[146:149], v[62:65]
	v_mfma_f32_16x16x32_bf16 v[54:57], v[138:141], v[146:149], v[54:57]
	v_mfma_f32_16x16x32_bf16 v[46:49], v[130:133], v[182:185], v[46:49]
	v_mfma_f32_16x16x32_bf16 v[38:41], v[138:141], v[182:185], v[38:41]
	s_barrier
	s_setprio 1
	v_mfma_f32_16x16x32_bf16 v[30:33], v[130:133], v[190:193], v[30:33]
	v_mfma_f32_16x16x32_bf16 v[22:25], v[138:141], v[190:193], v[22:25]
	v_mfma_f32_16x16x32_bf16 v[14:17], v[130:133], v[206:209], v[14:17]
	v_mfma_f32_16x16x32_bf16 v[6:9], v[138:141], v[206:209], v[6:9]
	v_mfma_f32_16x16x32_bf16 v[62:65], v[134:137], v[150:153], v[62:65]
	v_mfma_f32_16x16x32_bf16 v[54:57], v[142:145], v[150:153], v[54:57]
	v_mfma_f32_16x16x32_bf16 v[46:49], v[134:137], v[186:189], v[46:49]
	v_mfma_f32_16x16x32_bf16 v[38:41], v[142:145], v[186:189], v[38:41]
	v_mfma_f32_16x16x32_bf16 v[30:33], v[134:137], v[194:197], v[30:33]
	v_mfma_f32_16x16x32_bf16 v[22:25], v[142:145], v[194:197], v[22:25]
	v_mfma_f32_16x16x32_bf16 v[14:17], v[134:137], v[216:219], v[14:17]
	v_mfma_f32_16x16x32_bf16 v[6:9], v[142:145], v[216:219], v[6:9]
	v_mfma_f32_16x16x32_bf16 v[58:61], v[230:233], v[146:149], v[58:61]
	v_mfma_f32_16x16x32_bf16 v[50:53], v[238:241], v[146:149], v[50:53]
	v_mfma_f32_16x16x32_bf16 v[42:45], v[230:233], v[182:185], v[42:45]
	v_mfma_f32_16x16x32_bf16 v[34:37], v[238:241], v[182:185], v[34:37]
	v_mfma_f32_16x16x32_bf16 v[26:29], v[230:233], v[190:193], v[26:29]
	v_mfma_f32_16x16x32_bf16 v[18:21], v[238:241], v[190:193], v[18:21]
	v_mfma_f32_16x16x32_bf16 v[10:13], v[230:233], v[206:209], v[10:13]
	v_mfma_f32_16x16x32_bf16 v[2:5], v[238:241], v[206:209], v[2:5]
	v_mfma_f32_16x16x32_bf16 v[58:61], v[234:237], v[150:153], v[58:61]
	v_mfma_f32_16x16x32_bf16 v[50:53], v[242:245], v[150:153], v[50:53]
	v_mfma_f32_16x16x32_bf16 v[42:45], v[234:237], v[186:189], v[42:45]
	v_mfma_f32_16x16x32_bf16 v[34:37], v[242:245], v[186:189], v[34:37]
	v_mfma_f32_16x16x32_bf16 v[26:29], v[234:237], v[194:197], v[26:29]
	v_mfma_f32_16x16x32_bf16 v[18:21], v[242:245], v[194:197], v[18:21]
	v_mfma_f32_16x16x32_bf16 v[10:13], v[234:237], v[216:219], v[10:13]
	v_mfma_f32_16x16x32_bf16 v[2:5], v[242:245], v[216:219], v[2:5]
	s_setprio 0
	s_add_i32 s60, s60, 2
	s_add_u32 s28, s28, 0x100
	s_addc_u32 s29, s29, 0
	s_add_u32 s58, s58, 0x100
	s_addc_u32 s59, s59, 0
	s_cmp_gt_u32 s60, 13
	s_barrier
.LBB0_83:
	s_add_u32 s1, s28, 0xfffc0080
	s_addc_u32 s22, s29, -1
	s_add_i32 s23, 0, 0x10000
	v_add_u32_e32 v142, s23, v201
	ds_read_b128 v[130:133], v142
	ds_read_b128 v[134:137], v142 offset:1024
	ds_read_b128 v[138:141], v142 offset:2048
	ds_read_b128 v[142:145], v142 offset:3072
	s_cmp_eq_u32 s60, 12
	s_cselect_b32 s43, s27, s22
	s_cselect_b32 s42, s56, s1
	s_cselect_b32 s31, s7, s59
	s_cselect_b32 s30, s57, s58
	v_lshl_add_u64 v[176:177], s[28:29], 0, v[178:179]
	s_add_i32 m0, s46, 0xc000
	ds_read_b128 v[146:149], v205
	ds_read_b128 v[150:153], v205 offset:1024
	ds_read_b128 v[182:185], v205 offset:2048
	ds_read_b128 v[186:189], v205 offset:3072
	ds_read_b128 v[190:193], v205 offset:4096
	ds_read_b128 v[194:197], v205 offset:5120
	ds_read_b128 v[206:209], v205 offset:6144
	ds_read_b128 v[216:219], v205 offset:7168
	global_load_lds_dwordx4 v[176:177], off
	v_lshl_add_u64 v[176:177], s[28:29], 0, v[180:181]
	s_add_i32 m0, s46, 0xe000
	s_nop 0
	global_load_lds_dwordx4 v[176:177], off
	s_add_i32 s1, 0, 0x14000
	v_add_u32_e32 v168, s1, v201
	ds_read_b128 v[230:233], v168
	ds_read_b128 v[234:237], v168 offset:1024
	ds_read_b128 v[238:241], v168 offset:2048
	ds_read_b128 v[242:245], v168 offset:3072
	s_waitcnt vmcnt(8)
	s_waitcnt lgkmcnt(0)
	v_mfma_f32_16x16x32_bf16 v[126:129], v[130:133], v[146:149], v[126:129]
	v_mfma_f32_16x16x32_bf16 v[118:121], v[138:141], v[146:149], v[118:121]
	v_mfma_f32_16x16x32_bf16 v[110:113], v[130:133], v[182:185], v[110:113]
	v_mfma_f32_16x16x32_bf16 v[102:105], v[138:141], v[182:185], v[102:105]
	s_barrier
	s_setprio 1
	v_mfma_f32_16x16x32_bf16 v[94:97], v[130:133], v[190:193], v[94:97]
	v_mfma_f32_16x16x32_bf16 v[86:89], v[138:141], v[190:193], v[86:89]
	v_mfma_f32_16x16x32_bf16 v[78:81], v[130:133], v[206:209], v[78:81]
	v_mfma_f32_16x16x32_bf16 v[70:73], v[138:141], v[206:209], v[70:73]
	v_mfma_f32_16x16x32_bf16 v[126:129], v[134:137], v[150:153], v[126:129]
	v_mfma_f32_16x16x32_bf16 v[118:121], v[142:145], v[150:153], v[118:121]
	v_mfma_f32_16x16x32_bf16 v[110:113], v[134:137], v[186:189], v[110:113]
	v_mfma_f32_16x16x32_bf16 v[102:105], v[142:145], v[186:189], v[102:105]
	v_mfma_f32_16x16x32_bf16 v[94:97], v[134:137], v[194:197], v[94:97]
	v_mfma_f32_16x16x32_bf16 v[86:89], v[142:145], v[194:197], v[86:89]
	v_mfma_f32_16x16x32_bf16 v[78:81], v[134:137], v[216:219], v[78:81]
	v_mfma_f32_16x16x32_bf16 v[70:73], v[142:145], v[216:219], v[70:73]
	v_mfma_f32_16x16x32_bf16 v[122:125], v[230:233], v[146:149], v[122:125]
	v_mfma_f32_16x16x32_bf16 v[114:117], v[238:241], v[146:149], v[114:117]
	v_mfma_f32_16x16x32_bf16 v[106:109], v[230:233], v[182:185], v[106:109]
	v_mfma_f32_16x16x32_bf16 v[98:101], v[238:241], v[182:185], v[98:101]
	v_mfma_f32_16x16x32_bf16 v[90:93], v[230:233], v[190:193], v[90:93]
	v_mfma_f32_16x16x32_bf16 v[82:85], v[238:241], v[190:193], v[82:85]
	v_mfma_f32_16x16x32_bf16 v[74:77], v[230:233], v[206:209], v[74:77]
	v_mfma_f32_16x16x32_bf16 v[66:69], v[238:241], v[206:209], v[66:69]
	v_mfma_f32_16x16x32_bf16 v[122:125], v[234:237], v[150:153], v[122:125]
	v_mfma_f32_16x16x32_bf16 v[114:117], v[242:245], v[150:153], v[114:117]
	v_mfma_f32_16x16x32_bf16 v[106:109], v[234:237], v[186:189], v[106:109]
	v_mfma_f32_16x16x32_bf16 v[98:101], v[242:245], v[186:189], v[98:101]
	v_mfma_f32_16x16x32_bf16 v[90:93], v[234:237], v[194:197], v[90:93]
	v_mfma_f32_16x16x32_bf16 v[82:85], v[242:245], v[194:197], v[82:85]
	v_mfma_f32_16x16x32_bf16 v[74:77], v[234:237], v[216:219], v[74:77]
	v_mfma_f32_16x16x32_bf16 v[66:69], v[242:245], v[216:219], v[66:69]
	s_setprio 0
	s_barrier
	ds_read_b128 v[146:149], v205 offset:16384
	ds_read_b128 v[150:153], v205 offset:17408
	ds_read_b128 v[182:185], v205 offset:18432
	ds_read_b128 v[186:189], v205 offset:19456
	ds_read_b128 v[190:193], v205 offset:20480
	ds_read_b128 v[194:197], v205 offset:21504
	ds_read_b128 v[206:209], v205 offset:22528
	ds_read_b128 v[216:219], v205 offset:23552
	s_cbranch_vccz .Lss_i2
	v_lshlrev_b32_e32 v176, 4, v167
	s_lshl_b32 m0, s46, 1
	v_add_u32_e32 v176, s46, v176
	s_add_i32 m0, m0, 0x20000
	s_mov_b64 vcc, 0
	global_load_lds_dwordx4 v176, s[98:99]
	global_load_lds_dwordx4 v176, s[98:99] offset:1024
.Lss_i2:
	s_add_i32 s22, s23, s17
	v_lshl_add_u64 v[176:177], s[30:31], 0, v[0:1]
	s_mov_b32 m0, s22
	s_nop 0
	global_load_lds_dwordx4 v[176:177], off
	v_lshl_add_u64 v[202:203], s[30:31], 0, v[154:155]
	s_add_i32 m0, s22, 0x2000
	s_nop 0
	global_load_lds_dwordx4 v[202:203], off
	s_mov_b32 m0, s46
	v_lshl_add_u64 v[220:221], s[42:43], 0, v[158:159]
	global_load_lds_dwordx4 v[220:221], off
	v_lshl_add_u64 v[246:247], s[42:43], 0, v[156:157]
	s_mov_b32 m0, s47
	s_nop 0
	global_load_lds_dwordx4 v[246:247], off
	s_add_u32 s22, s30, 0x40000
	s_addc_u32 s23, s31, 0
	s_add_i32 s1, s1, s17
	s_mov_b32 m0, s1
	s_nop 0
	global_load_lds_dwordx4 v0, s[22:23]
	s_add_i32 m0, s1, 0x2000
	s_nop 0
	global_load_lds_dwordx4 v154, s[22:23]
	s_waitcnt vmcnt(8)
	s_waitcnt lgkmcnt(0)
	v_mfma_f32_16x16x32_bf16 v[62:65], v[130:133], v[146:149], v[62:65]
	v_mfma_f32_16x16x32_bf16 v[54:57], v[138:141], v[146:149], v[54:57]
	v_mfma_f32_16x16x32_bf16 v[46:49], v[130:133], v[182:185], v[46:49]
	v_mfma_f32_16x16x32_bf16 v[38:41], v[138:141], v[182:185], v[38:41]
	s_barrier
	s_setprio 1
	v_mfma_f32_16x16x32_bf16 v[30:33], v[130:133], v[190:193], v[30:33]
	v_mfma_f32_16x16x32_bf16 v[22:25], v[138:141], v[190:193], v[22:25]
	v_mfma_f32_16x16x32_bf16 v[14:17], v[130:133], v[206:209], v[14:17]
	v_mfma_f32_16x16x32_bf16 v[6:9], v[138:141], v[206:209], v[6:9]
	v_mfma_f32_16x16x32_bf16 v[62:65], v[134:137], v[150:153], v[62:65]
	v_mfma_f32_16x16x32_bf16 v[54:57], v[142:145], v[150:153], v[54:57]
	v_mfma_f32_16x16x32_bf16 v[46:49], v[134:137], v[186:189], v[46:49]
	v_mfma_f32_16x16x32_bf16 v[38:41], v[142:145], v[186:189], v[38:41]
	v_mfma_f32_16x16x32_bf16 v[30:33], v[134:137], v[194:197], v[30:33]
	v_mfma_f32_16x16x32_bf16 v[22:25], v[142:145], v[194:197], v[22:25]
	v_mfma_f32_16x16x32_bf16 v[14:17], v[134:137], v[216:219], v[14:17]
	v_mfma_f32_16x16x32_bf16 v[6:9], v[142:145], v[216:219], v[6:9]
	v_mfma_f32_16x16x32_bf16 v[58:61], v[230:233], v[146:149], v[58:61]
	v_mfma_f32_16x16x32_bf16 v[50:53], v[238:241], v[146:149], v[50:53]
	v_mfma_f32_16x16x32_bf16 v[42:45], v[230:233], v[182:185], v[42:45]
	v_mfma_f32_16x16x32_bf16 v[34:37], v[238:241], v[182:185], v[34:37]
	v_mfma_f32_16x16x32_bf16 v[26:29], v[230:233], v[190:193], v[26:29]
	v_mfma_f32_16x16x32_bf16 v[18:21], v[238:241], v[190:193], v[18:21]
	v_mfma_f32_16x16x32_bf16 v[10:13], v[230:233], v[206:209], v[10:13]
	v_mfma_f32_16x16x32_bf16 v[2:5], v[238:241], v[206:209], v[2:5]
	v_mfma_f32_16x16x32_bf16 v[58:61], v[234:237], v[150:153], v[58:61]
	v_mfma_f32_16x16x32_bf16 v[50:53], v[242:245], v[150:153], v[50:53]
	v_mfma_f32_16x16x32_bf16 v[42:45], v[234:237], v[186:189], v[42:45]
	v_mfma_f32_16x16x32_bf16 v[34:37], v[242:245], v[186:189], v[34:37]
	v_mfma_f32_16x16x32_bf16 v[26:29], v[234:237], v[194:197], v[26:29]
	v_mfma_f32_16x16x32_bf16 v[18:21], v[242:245], v[194:197], v[18:21]
	v_mfma_f32_16x16x32_bf16 v[10:13], v[234:237], v[216:219], v[10:13]
	v_mfma_f32_16x16x32_bf16 v[2:5], v[242:245], v[216:219], v[2:5]
	s_setprio 0
	s_barrier
	s_add_i32 s1, 0, 0x18000
	v_add_u32_e32 v142, s1, v201
	ds_read_b128 v[130:133], v142
	ds_read_b128 v[134:137], v142 offset:1024
	ds_read_b128 v[138:141], v142 offset:2048
	ds_read_b128 v[142:145], v142 offset:3072
	s_add_u32 s22, s42, 0x40000
	s_addc_u32 s23, s43, 0
	s_mov_b32 m0, s48
	v_lshl_add_u64 v[230:231], s[22:23], 0, v[158:159]
	ds_read_b128 v[146:149], v205 offset:32768
	ds_read_b128 v[150:153], v205 offset:33792
	ds_read_b128 v[182:185], v205 offset:34816
	ds_read_b128 v[186:189], v205 offset:35840
	ds_read_b128 v[190:193], v205 offset:36864
	ds_read_b128 v[194:197], v205 offset:37888
	ds_read_b128 v[206:209], v205 offset:38912
	ds_read_b128 v[216:219], v205 offset:39936
	global_load_lds_dwordx4 v[230:231], off
	v_lshl_add_u64 v[230:231], s[22:23], 0, v[156:157]
	s_mov_b32 m0, s49
	s_nop 0
	global_load_lds_dwordx4 v[230:231], off
	s_add_i32 s33, 0, 0x1c000
	v_add_u32_e32 v168, s33, v201
	ds_read_b128 v[230:233], v168
	ds_read_b128 v[234:237], v168 offset:1024
	ds_read_b128 v[238:241], v168 offset:2048
	ds_read_b128 v[242:245], v168 offset:3072
	s_waitcnt vmcnt(8)
	s_waitcnt lgkmcnt(0)
	v_mfma_f32_16x16x32_bf16 v[126:129], v[130:133], v[146:149], v[126:129]
	v_mfma_f32_16x16x32_bf16 v[118:121], v[138:141], v[146:149], v[118:121]
	v_mfma_f32_16x16x32_bf16 v[110:113], v[130:133], v[182:185], v[110:113]
	v_mfma_f32_16x16x32_bf16 v[102:105], v[138:141], v[182:185], v[102:105]
	s_barrier
	s_setprio 1
	v_mfma_f32_16x16x32_bf16 v[94:97], v[130:133], v[190:193], v[94:97]
	v_mfma_f32_16x16x32_bf16 v[86:89], v[138:141], v[190:193], v[86:89]
	v_mfma_f32_16x16x32_bf16 v[78:81], v[130:133], v[206:209], v[78:81]
	v_mfma_f32_16x16x32_bf16 v[70:73], v[138:141], v[206:209], v[70:73]
	v_mfma_f32_16x16x32_bf16 v[126:129], v[134:137], v[150:153], v[126:129]
	v_mfma_f32_16x16x32_bf16 v[118:121], v[142:145], v[150:153], v[118:121]
	v_mfma_f32_16x16x32_bf16 v[110:113], v[134:137], v[186:189], v[110:113]
	v_mfma_f32_16x16x32_bf16 v[102:105], v[142:145], v[186:189], v[102:105]
	v_mfma_f32_16x16x32_bf16 v[94:97], v[134:137], v[194:197], v[94:97]
	v_mfma_f32_16x16x32_bf16 v[86:89], v[142:145], v[194:197], v[86:89]
	v_mfma_f32_16x16x32_bf16 v[78:81], v[134:137], v[216:219], v[78:81]
	v_mfma_f32_16x16x32_bf16 v[70:73], v[142:145], v[216:219], v[70:73]
	v_mfma_f32_16x16x32_bf16 v[122:125], v[230:233], v[146:149], v[122:125]
	v_mfma_f32_16x16x32_bf16 v[114:117], v[238:241], v[146:149], v[114:117]
	v_mfma_f32_16x16x32_bf16 v[106:109], v[230:233], v[182:185], v[106:109]
	v_mfma_f32_16x16x32_bf16 v[98:101], v[238:241], v[182:185], v[98:101]
	v_mfma_f32_16x16x32_bf16 v[90:93], v[230:233], v[190:193], v[90:93]
	v_mfma_f32_16x16x32_bf16 v[82:85], v[238:241], v[190:193], v[82:85]
	v_mfma_f32_16x16x32_bf16 v[74:77], v[230:233], v[206:209], v[74:77]
	v_mfma_f32_16x16x32_bf16 v[66:69], v[238:241], v[206:209], v[66:69]
	v_mfma_f32_16x16x32_bf16 v[122:125], v[234:237], v[150:153], v[122:125]
	v_mfma_f32_16x16x32_bf16 v[114:117], v[242:245], v[150:153], v[114:117]
	v_mfma_f32_16x16x32_bf16 v[106:109], v[234:237], v[186:189], v[106:109]
	v_mfma_f32_16x16x32_bf16 v[98:101], v[242:245], v[186:189], v[98:101]
	v_mfma_f32_16x16x32_bf16 v[90:93], v[234:237], v[194:197], v[90:93]
	v_mfma_f32_16x16x32_bf16 v[82:85], v[242:245], v[194:197], v[82:85]
	v_mfma_f32_16x16x32_bf16 v[74:77], v[234:237], v[216:219], v[74:77]
	v_mfma_f32_16x16x32_bf16 v[66:69], v[242:245], v[216:219], v[66:69]
	s_setprio 0
	s_barrier
	ds_read_b128 v[146:149], v205 offset:49152
	ds_read_b128 v[150:153], v205 offset:50176
	ds_read_b128 v[182:185], v205 offset:51200
	ds_read_b128 v[186:189], v205 offset:52224
	ds_read_b128 v[190:193], v205 offset:53248
	ds_read_b128 v[194:197], v205 offset:54272
	ds_read_b128 v[206:209], v205 offset:55296
	ds_read_b128 v[216:219], v205 offset:56320
	s_add_i32 s1, s1, s17
	v_lshl_add_u64 v[176:177], v[176:177], 0, s[12:13]
	s_mov_b32 m0, s1
	s_nop 0
	global_load_lds_dwordx4 v[176:177], off
	v_lshl_add_u64 v[176:177], v[202:203], 0, s[12:13]
	s_add_i32 m0, s1, 0x2000
	s_nop 0
	global_load_lds_dwordx4 v[176:177], off
	s_mov_b32 m0, s20
	v_lshl_add_u64 v[176:177], v[220:221], 0, s[12:13]
	global_load_lds_dwordx4 v[176:177], off
	v_lshl_add_u64 v[176:177], v[246:247], 0, s[12:13]
	s_mov_b32 m0, s21
	s_nop 0
	global_load_lds_dwordx4 v[176:177], off
	s_add_u32 s22, s30, 0x40080
	s_addc_u32 s23, s31, 0
	s_add_i32 s1, s33, s17
	s_mov_b32 m0, s1
	s_nop 0
	global_load_lds_dwordx4 v0, s[22:23]
	s_add_i32 m0, s1, 0x2000
	s_nop 0
	global_load_lds_dwordx4 v154, s[22:23]
	s_waitcnt vmcnt(8)
	s_waitcnt lgkmcnt(0)
	v_mfma_f32_16x16x32_bf16 v[62:65], v[130:133], v[146:149], v[62:65]
	v_mfma_f32_16x16x32_bf16 v[54:57], v[138:141], v[146:149], v[54:57]
	v_mfma_f32_16x16x32_bf16 v[46:49], v[130:133], v[182:185], v[46:49]
	v_mfma_f32_16x16x32_bf16 v[38:41], v[138:141], v[182:185], v[38:41]
	s_barrier
	s_setprio 1
	v_mfma_f32_16x16x32_bf16 v[30:33], v[130:133], v[190:193], v[30:33]
	v_mfma_f32_16x16x32_bf16 v[22:25], v[138:141], v[190:193], v[22:25]
	v_mfma_f32_16x16x32_bf16 v[14:17], v[130:133], v[206:209], v[14:17]
	v_mfma_f32_16x16x32_bf16 v[6:9], v[138:141], v[206:209], v[6:9]
	v_mfma_f32_16x16x32_bf16 v[62:65], v[134:137], v[150:153], v[62:65]
	v_mfma_f32_16x16x32_bf16 v[54:57], v[142:145], v[150:153], v[54:57]
	v_mfma_f32_16x16x32_bf16 v[46:49], v[134:137], v[186:189], v[46:49]
	v_mfma_f32_16x16x32_bf16 v[38:41], v[142:145], v[186:189], v[38:41]
	v_mfma_f32_16x16x32_bf16 v[30:33], v[134:137], v[194:197], v[30:33]
	v_mfma_f32_16x16x32_bf16 v[22:25], v[142:145], v[194:197], v[22:25]
	v_mfma_f32_16x16x32_bf16 v[14:17], v[134:137], v[216:219], v[14:17]
	v_mfma_f32_16x16x32_bf16 v[6:9], v[142:145], v[216:219], v[6:9]
	v_mfma_f32_16x16x32_bf16 v[58:61], v[230:233], v[146:149], v[58:61]
	v_mfma_f32_16x16x32_bf16 v[50:53], v[238:241], v[146:149], v[50:53]
	v_mfma_f32_16x16x32_bf16 v[42:45], v[230:233], v[182:185], v[42:45]
	v_mfma_f32_16x16x32_bf16 v[34:37], v[238:241], v[182:185], v[34:37]
	v_mfma_f32_16x16x32_bf16 v[26:29], v[230:233], v[190:193], v[26:29]
	v_mfma_f32_16x16x32_bf16 v[18:21], v[238:241], v[190:193], v[18:21]
	v_mfma_f32_16x16x32_bf16 v[10:13], v[230:233], v[206:209], v[10:13]
	v_mfma_f32_16x16x32_bf16 v[2:5], v[238:241], v[206:209], v[2:5]
	v_mfma_f32_16x16x32_bf16 v[58:61], v[234:237], v[150:153], v[58:61]
	v_mfma_f32_16x16x32_bf16 v[50:53], v[242:245], v[150:153], v[50:53]
	v_mfma_f32_16x16x32_bf16 v[42:45], v[234:237], v[186:189], v[42:45]
	v_mfma_f32_16x16x32_bf16 v[34:37], v[242:245], v[186:189], v[34:37]
	v_mfma_f32_16x16x32_bf16 v[26:29], v[234:237], v[194:197], v[26:29]
	v_mfma_f32_16x16x32_bf16 v[18:21], v[242:245], v[194:197], v[18:21]
	v_mfma_f32_16x16x32_bf16 v[10:13], v[234:237], v[216:219], v[10:13]
	v_mfma_f32_16x16x32_bf16 v[2:5], v[242:245], v[216:219], v[2:5]
	s_setprio 0
	s_add_i32 s60, s60, 2
	s_add_u32 s28, s28, 0x100
	s_addc_u32 s29, s29, 0
	s_add_u32 s58, s58, 0x100
	s_addc_u32 s59, s59, 0
	s_cmp_gt_u32 s60, 13
	s_barrier
	s_cbranch_scc0 .LBB0_83
	s_cmpk_gt_u32 s0, 0xff
	s_cbranch_scc1 .Lrs_i2_post
	s_barrier

.Lrs_proj0_pre:
	s_add_u32 s1, s42, 0xfffc0080
	s_addc_u32 s22, s43, -1
	s_add_i32 s23, 0, 0x10000
	v_add_u32_e32 v142, s23, v217
	ds_read_b128 v[130:133], v142
	ds_read_b128 v[134:137], v142 offset:1024
	ds_read_b128 v[138:141], v142 offset:2048
	ds_read_b128 v[142:145], v142 offset:3072
	s_cmp_eq_u32 s54, 12
	s_cselect_b32 s45, s27, s22
	s_cselect_b32 s44, s50, s1
	s_cselect_b32 s31, s7, s53
	s_cselect_b32 s30, s51, s52
	v_lshl_add_u64 v[176:177], s[42:43], 0, v[190:191]
	s_add_i32 m0, s16, 0xc000
	ds_read_b128 v[146:149], v219
	ds_read_b128 v[150:153], v219 offset:1024
	ds_read_b128 v[154:157], v219 offset:2048
	ds_read_b128 v[158:161], v219 offset:3072
	ds_read_b128 v[194:197], v219 offset:4096
	ds_read_b128 v[198:201], v219 offset:5120
	ds_read_b128 v[202:205], v219 offset:6144
	ds_read_b128 v[206:209], v219 offset:7168
	global_load_lds_dwordx4 v[176:177], off
	v_lshl_add_u64 v[176:177], s[42:43], 0, v[192:193]
	s_add_i32 m0, s16, 0xe000
	s_nop 0
	global_load_lds_dwordx4 v[176:177], off
	s_add_i32 s1, 0, 0x14000
	v_add_u32_e32 v168, s1, v217
	ds_read_b128 v[230:233], v168
	ds_read_b128 v[234:237], v168 offset:1024
	ds_read_b128 v[238:241], v168 offset:2048
	ds_read_b128 v[242:245], v168 offset:3072
	s_waitcnt vmcnt(8)
	s_waitcnt lgkmcnt(0)
	v_mfma_f32_16x16x32_bf16 v[126:129], v[130:133], v[146:149], 0
	v_mfma_f32_16x16x32_bf16 v[122:125], v[138:141], v[146:149], 0
	v_mfma_f32_16x16x32_bf16 v[118:121], v[130:133], v[154:157], 0
	v_mfma_f32_16x16x32_bf16 v[110:113], v[138:141], v[154:157], 0
	s_barrier
	s_setprio 1
	v_mfma_f32_16x16x32_bf16 v[102:105], v[130:133], v[194:197], 0
	v_mfma_f32_16x16x32_bf16 v[94:97], v[138:141], v[194:197], 0
	v_mfma_f32_16x16x32_bf16 v[86:89], v[130:133], v[202:205], 0
	v_mfma_f32_16x16x32_bf16 v[78:81], v[138:141], v[202:205], 0
	v_mfma_f32_16x16x32_bf16 v[126:129], v[134:137], v[150:153], v[126:129]
	v_mfma_f32_16x16x32_bf16 v[122:125], v[142:145], v[150:153], v[122:125]
	v_mfma_f32_16x16x32_bf16 v[118:121], v[134:137], v[158:161], v[118:121]
	v_mfma_f32_16x16x32_bf16 v[110:113], v[142:145], v[158:161], v[110:113]
	v_mfma_f32_16x16x32_bf16 v[102:105], v[134:137], v[198:201], v[102:105]
	v_mfma_f32_16x16x32_bf16 v[94:97], v[142:145], v[198:201], v[94:97]
	v_mfma_f32_16x16x32_bf16 v[86:89], v[134:137], v[206:209], v[86:89]
	v_mfma_f32_16x16x32_bf16 v[78:81], v[142:145], v[206:209], v[78:81]
	v_mfma_f32_16x16x32_bf16 v[114:117], v[230:233], v[146:149], 0
	v_mfma_f32_16x16x32_bf16 v[106:109], v[238:241], v[146:149], 0
	v_mfma_f32_16x16x32_bf16 v[98:101], v[230:233], v[154:157], 0
	v_mfma_f32_16x16x32_bf16 v[90:93], v[238:241], v[154:157], 0
	v_mfma_f32_16x16x32_bf16 v[82:85], v[230:233], v[194:197], 0
	v_mfma_f32_16x16x32_bf16 v[74:77], v[238:241], v[194:197], 0
	v_mfma_f32_16x16x32_bf16 v[70:73], v[230:233], v[202:205], 0
	v_mfma_f32_16x16x32_bf16 v[66:69], v[238:241], v[202:205], 0
	v_mfma_f32_16x16x32_bf16 v[114:117], v[234:237], v[150:153], v[114:117]
	v_mfma_f32_16x16x32_bf16 v[106:109], v[242:245], v[150:153], v[106:109]
	v_mfma_f32_16x16x32_bf16 v[98:101], v[234:237], v[158:161], v[98:101]
	v_mfma_f32_16x16x32_bf16 v[90:93], v[242:245], v[158:161], v[90:93]
	v_mfma_f32_16x16x32_bf16 v[82:85], v[234:237], v[198:201], v[82:85]
	v_mfma_f32_16x16x32_bf16 v[74:77], v[242:245], v[198:201], v[74:77]
	v_mfma_f32_16x16x32_bf16 v[70:73], v[234:237], v[206:209], v[70:73]
	v_mfma_f32_16x16x32_bf16 v[66:69], v[242:245], v[206:209], v[66:69]
	s_setprio 0
	s_barrier
	ds_read_b128 v[146:149], v219 offset:16384
	ds_read_b128 v[150:153], v219 offset:17408
	ds_read_b128 v[154:157], v219 offset:18432
	ds_read_b128 v[158:161], v219 offset:19456
	ds_read_b128 v[194:197], v219 offset:20480
	ds_read_b128 v[198:201], v219 offset:21504
	ds_read_b128 v[202:205], v219 offset:22528
	ds_read_b128 v[206:209], v219 offset:23552
	s_cbranch_vccz .Lss_proj0
	v_lshlrev_b32_e32 v176, 4, v167
	s_lshl_b32 m0, s16, 1
	v_add_u32_e32 v176, s16, v176
	s_add_i32 m0, m0, 0x20000
	s_mov_b64 vcc, 0
	global_load_lds_dwordx4 v176, s[98:99]
	global_load_lds_dwordx4 v176, s[98:99] offset:1024
	s_add_i32 s22, s23, s4
	v_lshl_add_u64 v[176:177], s[30:31], 0, v[0:1]
	s_mov_b32 m0, s22
	s_nop 0
	global_load_lds_dwordx4 v[176:177], off
	v_lshl_add_u64 v[220:221], s[30:31], 0, v[178:179]
	s_add_i32 m0, s22, 0x2000
	s_nop 0
	global_load_lds_dwordx4 v[220:221], off
	s_mov_b32 m0, s16
	v_lshl_add_u64 v[246:247], s[44:45], 0, v[182:183]
	global_load_lds_dwordx4 v[246:247], off
	v_lshl_add_u64 v[248:249], s[44:45], 0, v[180:181]
	s_mov_b32 m0, s17
	s_nop 0
	global_load_lds_dwordx4 v[248:249], off
	s_add_u32 s22, s30, 0x40000
	s_addc_u32 s23, s31, 0
	s_add_i32 s1, s1, s4
	s_mov_b32 m0, s1
	s_nop 0
	global_load_lds_dwordx4 v0, s[22:23]
	s_add_i32 m0, s1, 0x2000
	s_nop 0
	global_load_lds_dwordx4 v178, s[22:23]
	s_waitcnt vmcnt(8)
	s_waitcnt lgkmcnt(0)
	v_mfma_f32_16x16x32_bf16 v[62:65], v[130:133], v[146:149], 0
	v_mfma_f32_16x16x32_bf16 v[58:61], v[138:141], v[146:149], 0
	v_mfma_f32_16x16x32_bf16 v[54:57], v[130:133], v[154:157], 0
	v_mfma_f32_16x16x32_bf16 v[46:49], v[138:141], v[154:157], 0
	s_barrier
	s_setprio 1
	v_mfma_f32_16x16x32_bf16 v[38:41], v[130:133], v[194:197], 0
	v_mfma_f32_16x16x32_bf16 v[30:33], v[138:141], v[194:197], 0
	v_mfma_f32_16x16x32_bf16 v[22:25], v[130:133], v[202:205], 0
	v_mfma_f32_16x16x32_bf16 v[14:17], v[138:141], v[202:205], 0
	v_mfma_f32_16x16x32_bf16 v[62:65], v[134:137], v[150:153], v[62:65]
	v_mfma_f32_16x16x32_bf16 v[58:61], v[142:145], v[150:153], v[58:61]
	v_mfma_f32_16x16x32_bf16 v[54:57], v[134:137], v[158:161], v[54:57]
	v_mfma_f32_16x16x32_bf16 v[46:49], v[142:145], v[158:161], v[46:49]
	v_mfma_f32_16x16x32_bf16 v[38:41], v[134:137], v[198:201], v[38:41]
	v_mfma_f32_16x16x32_bf16 v[30:33], v[142:145], v[198:201], v[30:33]
	v_mfma_f32_16x16x32_bf16 v[22:25], v[134:137], v[206:209], v[22:25]
	v_mfma_f32_16x16x32_bf16 v[14:17], v[142:145], v[206:209], v[14:17]
	v_mfma_f32_16x16x32_bf16 v[50:53], v[230:233], v[146:149], 0
	v_mfma_f32_16x16x32_bf16 v[42:45], v[238:241], v[146:149], 0
	v_mfma_f32_16x16x32_bf16 v[34:37], v[230:233], v[154:157], 0
	v_mfma_f32_16x16x32_bf16 v[26:29], v[238:241], v[154:157], 0
	v_mfma_f32_16x16x32_bf16 v[18:21], v[230:233], v[194:197], 0
	v_mfma_f32_16x16x32_bf16 v[10:13], v[238:241], v[194:197], 0
	v_mfma_f32_16x16x32_bf16 v[6:9], v[230:233], v[202:205], 0
	v_mfma_f32_16x16x32_bf16 v[2:5], v[238:241], v[202:205], 0
	v_mfma_f32_16x16x32_bf16 v[50:53], v[234:237], v[150:153], v[50:53]
	v_mfma_f32_16x16x32_bf16 v[42:45], v[242:245], v[150:153], v[42:45]
	v_mfma_f32_16x16x32_bf16 v[34:37], v[234:237], v[158:161], v[34:37]
	v_mfma_f32_16x16x32_bf16 v[26:29], v[242:245], v[158:161], v[26:29]
	v_mfma_f32_16x16x32_bf16 v[18:21], v[234:237], v[198:201], v[18:21]
	v_mfma_f32_16x16x32_bf16 v[10:13], v[242:245], v[198:201], v[10:13]
	v_mfma_f32_16x16x32_bf16 v[6:9], v[234:237], v[206:209], v[6:9]
	v_mfma_f32_16x16x32_bf16 v[2:5], v[242:245], v[206:209], v[2:5]
	s_setprio 0
	s_barrier
	s_add_i32 s1, 0, 0x18000
	v_add_u32_e32 v142, s1, v217
	ds_read_b128 v[130:133], v142
	ds_read_b128 v[134:137], v142 offset:1024
	ds_read_b128 v[138:141], v142 offset:2048
	ds_read_b128 v[142:145], v142 offset:3072
	s_add_u32 s22, s44, 0x40000
	s_addc_u32 s23, s45, 0
	s_mov_b32 m0, s20
	v_lshl_add_u64 v[230:231], s[22:23], 0, v[182:183]
	ds_read_b128 v[146:149], v219 offset:32768
	ds_read_b128 v[150:153], v219 offset:33792
	ds_read_b128 v[154:157], v219 offset:34816
	ds_read_b128 v[158:161], v219 offset:35840
	ds_read_b128 v[194:197], v219 offset:36864
	ds_read_b128 v[198:201], v219 offset:37888
	ds_read_b128 v[202:205], v219 offset:38912
	ds_read_b128 v[206:209], v219 offset:39936
	global_load_lds_dwordx4 v[230:231], off
	v_lshl_add_u64 v[230:231], s[22:23], 0, v[180:181]
	s_mov_b32 m0, s21
	s_nop 0
	global_load_lds_dwordx4 v[230:231], off
	s_add_i32 s33, 0, 0x1c000
	v_add_u32_e32 v168, s33, v217
	ds_read_b128 v[230:233], v168
	ds_read_b128 v[234:237], v168 offset:1024
	ds_read_b128 v[238:241], v168 offset:2048
	ds_read_b128 v[242:245], v168 offset:3072
	s_waitcnt vmcnt(8)
	s_waitcnt lgkmcnt(0)
	v_mfma_f32_16x16x32_bf16 v[126:129], v[130:133], v[146:149], v[126:129]
	v_mfma_f32_16x16x32_bf16 v[122:125], v[138:141], v[146:149], v[122:125]
	v_mfma_f32_16x16x32_bf16 v[118:121], v[130:133], v[154:157], v[118:121]
	v_mfma_f32_16x16x32_bf16 v[110:113], v[138:141], v[154:157], v[110:113]
	s_barrier
	s_setprio 1
	v_mfma_f32_16x16x32_bf16 v[102:105], v[130:133], v[194:197], v[102:105]
	v_mfma_f32_16x16x32_bf16 v[94:97], v[138:141], v[194:197], v[94:97]
	v_mfma_f32_16x16x32_bf16 v[86:89], v[130:133], v[202:205], v[86:89]
	v_mfma_f32_16x16x32_bf16 v[78:81], v[138:141], v[202:205], v[78:81]
	v_mfma_f32_16x16x32_bf16 v[126:129], v[134:137], v[150:153], v[126:129]
	v_mfma_f32_16x16x32_bf16 v[122:125], v[142:145], v[150:153], v[122:125]
	v_mfma_f32_16x16x32_bf16 v[118:121], v[134:137], v[158:161], v[118:121]
	v_mfma_f32_16x16x32_bf16 v[110:113], v[142:145], v[158:161], v[110:113]
	v_mfma_f32_16x16x32_bf16 v[102:105], v[134:137], v[198:201], v[102:105]
	v_mfma_f32_16x16x32_bf16 v[94:97], v[142:145], v[198:201], v[94:97]
	v_mfma_f32_16x16x32_bf16 v[86:89], v[134:137], v[206:209], v[86:89]
	v_mfma_f32_16x16x32_bf16 v[78:81], v[142:145], v[206:209], v[78:81]
	v_mfma_f32_16x16x32_bf16 v[114:117], v[230:233], v[146:149], v[114:117]
	v_mfma_f32_16x16x32_bf16 v[106:109], v[238:241], v[146:149], v[106:109]
	v_mfma_f32_16x16x32_bf16 v[98:101], v[230:233], v[154:157], v[98:101]
	v_mfma_f32_16x16x32_bf16 v[90:93], v[238:241], v[154:157], v[90:93]
	v_mfma_f32_16x16x32_bf16 v[82:85], v[230:233], v[194:197], v[82:85]
	v_mfma_f32_16x16x32_bf16 v[74:77], v[238:241], v[194:197], v[74:77]
	v_mfma_f32_16x16x32_bf16 v[70:73], v[230:233], v[202:205], v[70:73]
	v_mfma_f32_16x16x32_bf16 v[66:69], v[238:241], v[202:205], v[66:69]
	v_mfma_f32_16x16x32_bf16 v[114:117], v[234:237], v[150:153], v[114:117]
	v_mfma_f32_16x16x32_bf16 v[106:109], v[242:245], v[150:153], v[106:109]
	v_mfma_f32_16x16x32_bf16 v[98:101], v[234:237], v[158:161], v[98:101]
	v_mfma_f32_16x16x32_bf16 v[90:93], v[242:245], v[158:161], v[90:93]
	v_mfma_f32_16x16x32_bf16 v[82:85], v[234:237], v[198:201], v[82:85]
	v_mfma_f32_16x16x32_bf16 v[74:77], v[242:245], v[198:201], v[74:77]
	v_mfma_f32_16x16x32_bf16 v[70:73], v[234:237], v[206:209], v[70:73]
	v_mfma_f32_16x16x32_bf16 v[66:69], v[242:245], v[206:209], v[66:69]
	s_setprio 0
	s_barrier
	ds_read_b128 v[146:149], v219 offset:49152
	ds_read_b128 v[150:153], v219 offset:50176
	ds_read_b128 v[154:157], v219 offset:51200
	ds_read_b128 v[158:161], v219 offset:52224
	ds_read_b128 v[194:197], v219 offset:53248
	ds_read_b128 v[198:201], v219 offset:54272
	ds_read_b128 v[202:205], v219 offset:55296
	ds_read_b128 v[206:209], v219 offset:56320
	s_add_i32 s1, s1, s4
	v_lshl_add_u64 v[176:177], v[176:177], 0, s[12:13]
	s_mov_b32 m0, s1
	s_nop 0
	global_load_lds_dwordx4 v[176:177], off
	v_lshl_add_u64 v[176:177], v[220:221], 0, s[12:13]
	s_add_i32 m0, s1, 0x2000
	s_nop 0
	global_load_lds_dwordx4 v[176:177], off
	s_mov_b32 m0, s34
	v_lshl_add_u64 v[176:177], v[246:247], 0, s[12:13]
	global_load_lds_dwordx4 v[176:177], off
	v_lshl_add_u64 v[176:177], v[248:249], 0, s[12:13]
	s_mov_b32 m0, s46
	s_nop 0
	global_load_lds_dwordx4 v[176:177], off
	s_add_u32 s22, s30, 0x40080
	s_addc_u32 s23, s31, 0
	s_add_i32 s1, s33, s4
	s_mov_b32 m0, s1
	s_nop 0
	global_load_lds_dwordx4 v0, s[22:23]
	s_add_i32 m0, s1, 0x2000
	s_nop 0
	global_load_lds_dwordx4 v178, s[22:23]
	s_waitcnt vmcnt(8)
	s_waitcnt lgkmcnt(0)
	v_mfma_f32_16x16x32_bf16 v[62:65], v[130:133], v[146:149], v[62:65]
	v_mfma_f32_16x16x32_bf16 v[58:61], v[138:141], v[146:149], v[58:61]
	v_mfma_f32_16x16x32_bf16 v[54:57], v[130:133], v[154:157], v[54:57]
	v_mfma_f32_16x16x32_bf16 v[46:49], v[138:141], v[154:157], v[46:49]
	s_barrier
	s_setprio 1
	v_mfma_f32_16x16x32_bf16 v[38:41], v[130:133], v[194:197], v[38:41]
	v_mfma_f32_16x16x32_bf16 v[30:33], v[138:141], v[194:197], v[30:33]
	v_mfma_f32_16x16x32_bf16 v[22:25], v[130:133], v[202:205], v[22:25]
	v_mfma_f32_16x16x32_bf16 v[14:17], v[138:141], v[202:205], v[14:17]
	v_mfma_f32_16x16x32_bf16 v[62:65], v[134:137], v[150:153], v[62:65]
	v_mfma_f32_16x16x32_bf16 v[58:61], v[142:145], v[150:153], v[58:61]
	v_mfma_f32_16x16x32_bf16 v[54:57], v[134:137], v[158:161], v[54:57]
	v_mfma_f32_16x16x32_bf16 v[46:49], v[142:145], v[158:161], v[46:49]
	v_mfma_f32_16x16x32_bf16 v[38:41], v[134:137], v[198:201], v[38:41]
	v_mfma_f32_16x16x32_bf16 v[30:33], v[142:145], v[198:201], v[30:33]
	v_mfma_f32_16x16x32_bf16 v[22:25], v[134:137], v[206:209], v[22:25]
	v_mfma_f32_16x16x32_bf16 v[14:17], v[142:145], v[206:209], v[14:17]
	v_mfma_f32_16x16x32_bf16 v[50:53], v[230:233], v[146:149], v[50:53]
	v_mfma_f32_16x16x32_bf16 v[42:45], v[238:241], v[146:149], v[42:45]
	v_mfma_f32_16x16x32_bf16 v[34:37], v[230:233], v[154:157], v[34:37]
	v_mfma_f32_16x16x32_bf16 v[26:29], v[238:241], v[154:157], v[26:29]
	v_mfma_f32_16x16x32_bf16 v[18:21], v[230:233], v[194:197], v[18:21]
	v_mfma_f32_16x16x32_bf16 v[10:13], v[238:241], v[194:197], v[10:13]
	v_mfma_f32_16x16x32_bf16 v[6:9], v[230:233], v[202:205], v[6:9]
	v_mfma_f32_16x16x32_bf16 v[2:5], v[238:241], v[202:205], v[2:5]
	v_mfma_f32_16x16x32_bf16 v[50:53], v[234:237], v[150:153], v[50:53]
	v_mfma_f32_16x16x32_bf16 v[42:45], v[242:245], v[150:153], v[42:45]
	v_mfma_f32_16x16x32_bf16 v[34:37], v[234:237], v[158:161], v[34:37]
	v_mfma_f32_16x16x32_bf16 v[26:29], v[242:245], v[158:161], v[26:29]
	v_mfma_f32_16x16x32_bf16 v[18:21], v[234:237], v[198:201], v[18:21]
	v_mfma_f32_16x16x32_bf16 v[10:13], v[242:245], v[198:201], v[10:13]
	v_mfma_f32_16x16x32_bf16 v[6:9], v[234:237], v[206:209], v[6:9]
	v_mfma_f32_16x16x32_bf16 v[2:5], v[242:245], v[206:209], v[2:5]
	s_setprio 0
	s_add_i32 s54, s54, 2
	s_add_u32 s42, s42, 0x100
	s_addc_u32 s43, s43, 0
	s_add_u32 s52, s52, 0x100
	s_addc_u32 s53, s53, 0
	s_cmp_gt_u32 s54, 13
	s_barrier
.LBB0_289:
	s_add_u32 s1, s42, 0xfffc0080
	s_addc_u32 s22, s43, -1
	s_add_i32 s23, 0, 0x10000
	v_add_u32_e32 v142, s23, v217
	ds_read_b128 v[130:133], v142
	ds_read_b128 v[134:137], v142 offset:1024
	ds_read_b128 v[138:141], v142 offset:2048
	ds_read_b128 v[142:145], v142 offset:3072
	s_cmp_eq_u32 s54, 12
	s_cselect_b32 s45, s27, s22
	s_cselect_b32 s44, s50, s1
	s_cselect_b32 s31, s7, s53
	s_cselect_b32 s30, s51, s52
	v_lshl_add_u64 v[176:177], s[42:43], 0, v[190:191]
	s_add_i32 m0, s16, 0xc000
	ds_read_b128 v[146:149], v219
	ds_read_b128 v[150:153], v219 offset:1024
	ds_read_b128 v[154:157], v219 offset:2048
	ds_read_b128 v[158:161], v219 offset:3072
	ds_read_b128 v[194:197], v219 offset:4096
	ds_read_b128 v[198:201], v219 offset:5120
	ds_read_b128 v[202:205], v219 offset:6144
	ds_read_b128 v[206:209], v219 offset:7168
	global_load_lds_dwordx4 v[176:177], off
	v_lshl_add_u64 v[176:177], s[42:43], 0, v[192:193]
	s_add_i32 m0, s16, 0xe000
	s_nop 0
	global_load_lds_dwordx4 v[176:177], off
	s_add_i32 s1, 0, 0x14000
	v_add_u32_e32 v168, s1, v217
	ds_read_b128 v[230:233], v168
	ds_read_b128 v[234:237], v168 offset:1024
	ds_read_b128 v[238:241], v168 offset:2048
	ds_read_b128 v[242:245], v168 offset:3072
	s_waitcnt vmcnt(8)
	s_waitcnt lgkmcnt(0)
	v_mfma_f32_16x16x32_bf16 v[126:129], v[130:133], v[146:149], v[126:129]
	v_mfma_f32_16x16x32_bf16 v[122:125], v[138:141], v[146:149], v[122:125]
	v_mfma_f32_16x16x32_bf16 v[118:121], v[130:133], v[154:157], v[118:121]
	v_mfma_f32_16x16x32_bf16 v[110:113], v[138:141], v[154:157], v[110:113]
	s_barrier
	s_setprio 1
	v_mfma_f32_16x16x32_bf16 v[102:105], v[130:133], v[194:197], v[102:105]
	v_mfma_f32_16x16x32_bf16 v[94:97], v[138:141], v[194:197], v[94:97]
	v_mfma_f32_16x16x32_bf16 v[86:89], v[130:133], v[202:205], v[86:89]
	v_mfma_f32_16x16x32_bf16 v[78:81], v[138:141], v[202:205], v[78:81]
	v_mfma_f32_16x16x32_bf16 v[126:129], v[134:137], v[150:153], v[126:129]
	v_mfma_f32_16x16x32_bf16 v[122:125], v[142:145], v[150:153], v[122:125]
	v_mfma_f32_16x16x32_bf16 v[118:121], v[134:137], v[158:161], v[118:121]
	v_mfma_f32_16x16x32_bf16 v[110:113], v[142:145], v[158:161], v[110:113]
	v_mfma_f32_16x16x32_bf16 v[102:105], v[134:137], v[198:201], v[102:105]
	v_mfma_f32_16x16x32_bf16 v[94:97], v[142:145], v[198:201], v[94:97]
	v_mfma_f32_16x16x32_bf16 v[86:89], v[134:137], v[206:209], v[86:89]
	v_mfma_f32_16x16x32_bf16 v[78:81], v[142:145], v[206:209], v[78:81]
	v_mfma_f32_16x16x32_bf16 v[114:117], v[230:233], v[146:149], v[114:117]
	v_mfma_f32_16x16x32_bf16 v[106:109], v[238:241], v[146:149], v[106:109]
	v_mfma_f32_16x16x32_bf16 v[98:101], v[230:233], v[154:157], v[98:101]
	v_mfma_f32_16x16x32_bf16 v[90:93], v[238:241], v[154:157], v[90:93]
	v_mfma_f32_16x16x32_bf16 v[82:85], v[230:233], v[194:197], v[82:85]
	v_mfma_f32_16x16x32_bf16 v[74:77], v[238:241], v[194:197], v[74:77]
	v_mfma_f32_16x16x32_bf16 v[70:73], v[230:233], v[202:205], v[70:73]
	v_mfma_f32_16x16x32_bf16 v[66:69], v[238:241], v[202:205], v[66:69]
	v_mfma_f32_16x16x32_bf16 v[114:117], v[234:237], v[150:153], v[114:117]
	v_mfma_f32_16x16x32_bf16 v[106:109], v[242:245], v[150:153], v[106:109]
	v_mfma_f32_16x16x32_bf16 v[98:101], v[234:237], v[158:161], v[98:101]
	v_mfma_f32_16x16x32_bf16 v[90:93], v[242:245], v[158:161], v[90:93]
	v_mfma_f32_16x16x32_bf16 v[82:85], v[234:237], v[198:201], v[82:85]
	v_mfma_f32_16x16x32_bf16 v[74:77], v[242:245], v[198:201], v[74:77]
	v_mfma_f32_16x16x32_bf16 v[70:73], v[234:237], v[206:209], v[70:73]
	v_mfma_f32_16x16x32_bf16 v[66:69], v[242:245], v[206:209], v[66:69]
	s_setprio 0
	s_barrier
	ds_read_b128 v[146:149], v219 offset:16384
	ds_read_b128 v[150:153], v219 offset:17408
	ds_read_b128 v[154:157], v219 offset:18432
	ds_read_b128 v[158:161], v219 offset:19456
	ds_read_b128 v[194:197], v219 offset:20480
	ds_read_b128 v[198:201], v219 offset:21504
	ds_read_b128 v[202:205], v219 offset:22528
	ds_read_b128 v[206:209], v219 offset:23552
	s_cbranch_vccz .Lss_proj0
	v_lshlrev_b32_e32 v176, 4, v167
	s_lshl_b32 m0, s16, 1
	v_add_u32_e32 v176, s16, v176
	s_add_i32 m0, m0, 0x20000
	s_mov_b64 vcc, 0
	global_load_lds_dwordx4 v176, s[98:99]
	global_load_lds_dwordx4 v176, s[98:99] offset:1024
.Lss_proj0:
	s_add_i32 s22, s23, s4
	v_lshl_add_u64 v[176:177], s[30:31], 0, v[0:1]
	s_mov_b32 m0, s22
	s_nop 0
	global_load_lds_dwordx4 v[176:177], off
	v_lshl_add_u64 v[220:221], s[30:31], 0, v[178:179]
	s_add_i32 m0, s22, 0x2000
	s_nop 0
	global_load_lds_dwordx4 v[220:221], off
	s_mov_b32 m0, s16
	v_lshl_add_u64 v[246:247], s[44:45], 0, v[182:183]
	global_load_lds_dwordx4 v[246:247], off
	v_lshl_add_u64 v[248:249], s[44:45], 0, v[180:181]
	s_mov_b32 m0, s17
	s_nop 0
	global_load_lds_dwordx4 v[248:249], off
	s_add_u32 s22, s30, 0x40000
	s_addc_u32 s23, s31, 0
	s_add_i32 s1, s1, s4
	s_mov_b32 m0, s1
	s_nop 0
	global_load_lds_dwordx4 v0, s[22:23]
	s_add_i32 m0, s1, 0x2000
	s_nop 0
	global_load_lds_dwordx4 v178, s[22:23]
	s_waitcnt vmcnt(8)
	s_waitcnt lgkmcnt(0)
	v_mfma_f32_16x16x32_bf16 v[62:65], v[130:133], v[146:149], v[62:65]
	v_mfma_f32_16x16x32_bf16 v[58:61], v[138:141], v[146:149], v[58:61]
	v_mfma_f32_16x16x32_bf16 v[54:57], v[130:133], v[154:157], v[54:57]
	v_mfma_f32_16x16x32_bf16 v[46:49], v[138:141], v[154:157], v[46:49]
	s_barrier
	s_setprio 1
	v_mfma_f32_16x16x32_bf16 v[38:41], v[130:133], v[194:197], v[38:41]
	v_mfma_f32_16x16x32_bf16 v[30:33], v[138:141], v[194:197], v[30:33]
	v_mfma_f32_16x16x32_bf16 v[22:25], v[130:133], v[202:205], v[22:25]
	v_mfma_f32_16x16x32_bf16 v[14:17], v[138:141], v[202:205], v[14:17]
	v_mfma_f32_16x16x32_bf16 v[62:65], v[134:137], v[150:153], v[62:65]
	v_mfma_f32_16x16x32_bf16 v[58:61], v[142:145], v[150:153], v[58:61]
	v_mfma_f32_16x16x32_bf16 v[54:57], v[134:137], v[158:161], v[54:57]
	v_mfma_f32_16x16x32_bf16 v[46:49], v[142:145], v[158:161], v[46:49]
	v_mfma_f32_16x16x32_bf16 v[38:41], v[134:137], v[198:201], v[38:41]
	v_mfma_f32_16x16x32_bf16 v[30:33], v[142:145], v[198:201], v[30:33]
	v_mfma_f32_16x16x32_bf16 v[22:25], v[134:137], v[206:209], v[22:25]
	v_mfma_f32_16x16x32_bf16 v[14:17], v[142:145], v[206:209], v[14:17]
	v_mfma_f32_16x16x32_bf16 v[50:53], v[230:233], v[146:149], v[50:53]
	v_mfma_f32_16x16x32_bf16 v[42:45], v[238:241], v[146:149], v[42:45]
	v_mfma_f32_16x16x32_bf16 v[34:37], v[230:233], v[154:157], v[34:37]
	v_mfma_f32_16x16x32_bf16 v[26:29], v[238:241], v[154:157], v[26:29]
	v_mfma_f32_16x16x32_bf16 v[18:21], v[230:233], v[194:197], v[18:21]
	v_mfma_f32_16x16x32_bf16 v[10:13], v[238:241], v[194:197], v[10:13]
	v_mfma_f32_16x16x32_bf16 v[6:9], v[230:233], v[202:205], v[6:9]
	v_mfma_f32_16x16x32_bf16 v[2:5], v[238:241], v[202:205], v[2:5]
	v_mfma_f32_16x16x32_bf16 v[50:53], v[234:237], v[150:153], v[50:53]
	v_mfma_f32_16x16x32_bf16 v[42:45], v[242:245], v[150:153], v[42:45]
	v_mfma_f32_16x16x32_bf16 v[34:37], v[234:237], v[158:161], v[34:37]
	v_mfma_f32_16x16x32_bf16 v[26:29], v[242:245], v[158:161], v[26:29]
	v_mfma_f32_16x16x32_bf16 v[18:21], v[234:237], v[198:201], v[18:21]
	v_mfma_f32_16x16x32_bf16 v[10:13], v[242:245], v[198:201], v[10:13]
	v_mfma_f32_16x16x32_bf16 v[6:9], v[234:237], v[206:209], v[6:9]
	v_mfma_f32_16x16x32_bf16 v[2:5], v[242:245], v[206:209], v[2:5]
	s_setprio 0
	s_barrier
	s_add_i32 s1, 0, 0x18000
	v_add_u32_e32 v142, s1, v217
	ds_read_b128 v[130:133], v142
	ds_read_b128 v[134:137], v142 offset:1024
	ds_read_b128 v[138:141], v142 offset:2048
	ds_read_b128 v[142:145], v142 offset:3072
	s_add_u32 s22, s44, 0x40000
	s_addc_u32 s23, s45, 0
	s_mov_b32 m0, s20
	v_lshl_add_u64 v[230:231], s[22:23], 0, v[182:183]
	ds_read_b128 v[146:149], v219 offset:32768
	ds_read_b128 v[150:153], v219 offset:33792
	ds_read_b128 v[154:157], v219 offset:34816
	ds_read_b128 v[158:161], v219 offset:35840
	ds_read_b128 v[194:197], v219 offset:36864
	ds_read_b128 v[198:201], v219 offset:37888
	ds_read_b128 v[202:205], v219 offset:38912
	ds_read_b128 v[206:209], v219 offset:39936
	global_load_lds_dwordx4 v[230:231], off
	v_lshl_add_u64 v[230:231], s[22:23], 0, v[180:181]
	s_mov_b32 m0, s21
	s_nop 0
	global_load_lds_dwordx4 v[230:231], off
	s_add_i32 s33, 0, 0x1c000
	v_add_u32_e32 v168, s33, v217
	ds_read_b128 v[230:233], v168
	ds_read_b128 v[234:237], v168 offset:1024
	ds_read_b128 v[238:241], v168 offset:2048
	ds_read_b128 v[242:245], v168 offset:3072
	s_waitcnt vmcnt(8)
	s_waitcnt lgkmcnt(0)
	v_mfma_f32_16x16x32_bf16 v[126:129], v[130:133], v[146:149], v[126:129]
	v_mfma_f32_16x16x32_bf16 v[122:125], v[138:141], v[146:149], v[122:125]
	v_mfma_f32_16x16x32_bf16 v[118:121], v[130:133], v[154:157], v[118:121]
	v_mfma_f32_16x16x32_bf16 v[110:113], v[138:141], v[154:157], v[110:113]
	s_barrier
	s_setprio 1
	v_mfma_f32_16x16x32_bf16 v[102:105], v[130:133], v[194:197], v[102:105]
	v_mfma_f32_16x16x32_bf16 v[94:97], v[138:141], v[194:197], v[94:97]
	v_mfma_f32_16x16x32_bf16 v[86:89], v[130:133], v[202:205], v[86:89]
	v_mfma_f32_16x16x32_bf16 v[78:81], v[138:141], v[202:205], v[78:81]
	v_mfma_f32_16x16x32_bf16 v[126:129], v[134:137], v[150:153], v[126:129]
	v_mfma_f32_16x16x32_bf16 v[122:125], v[142:145], v[150:153], v[122:125]
	v_mfma_f32_16x16x32_bf16 v[118:121], v[134:137], v[158:161], v[118:121]
	v_mfma_f32_16x16x32_bf16 v[110:113], v[142:145], v[158:161], v[110:113]
	v_mfma_f32_16x16x32_bf16 v[102:105], v[134:137], v[198:201], v[102:105]
	v_mfma_f32_16x16x32_bf16 v[94:97], v[142:145], v[198:201], v[94:97]
	v_mfma_f32_16x16x32_bf16 v[86:89], v[134:137], v[206:209], v[86:89]
	v_mfma_f32_16x16x32_bf16 v[78:81], v[142:145], v[206:209], v[78:81]
	v_mfma_f32_16x16x32_bf16 v[114:117], v[230:233], v[146:149], v[114:117]
	v_mfma_f32_16x16x32_bf16 v[106:109], v[238:241], v[146:149], v[106:109]
	v_mfma_f32_16x16x32_bf16 v[98:101], v[230:233], v[154:157], v[98:101]
	v_mfma_f32_16x16x32_bf16 v[90:93], v[238:241], v[154:157], v[90:93]
	v_mfma_f32_16x16x32_bf16 v[82:85], v[230:233], v[194:197], v[82:85]
	v_mfma_f32_16x16x32_bf16 v[74:77], v[238:241], v[194:197], v[74:77]
	v_mfma_f32_16x16x32_bf16 v[70:73], v[230:233], v[202:205], v[70:73]
	v_mfma_f32_16x16x32_bf16 v[66:69], v[238:241], v[202:205], v[66:69]
	v_mfma_f32_16x16x32_bf16 v[114:117], v[234:237], v[150:153], v[114:117]
	v_mfma_f32_16x16x32_bf16 v[106:109], v[242:245], v[150:153], v[106:109]
	v_mfma_f32_16x16x32_bf16 v[98:101], v[234:237], v[158:161], v[98:101]
	v_mfma_f32_16x16x32_bf16 v[90:93], v[242:245], v[158:161], v[90:93]
	v_mfma_f32_16x16x32_bf16 v[82:85], v[234:237], v[198:201], v[82:85]
	v_mfma_f32_16x16x32_bf16 v[74:77], v[242:245], v[198:201], v[74:77]
	v_mfma_f32_16x16x32_bf16 v[70:73], v[234:237], v[206:209], v[70:73]
	v_mfma_f32_16x16x32_bf16 v[66:69], v[242:245], v[206:209], v[66:69]
	s_setprio 0
	s_barrier
	ds_read_b128 v[146:149], v219 offset:49152
	ds_read_b128 v[150:153], v219 offset:50176
	ds_read_b128 v[154:157], v219 offset:51200
	ds_read_b128 v[158:161], v219 offset:52224
	ds_read_b128 v[194:197], v219 offset:53248
	ds_read_b128 v[198:201], v219 offset:54272
	ds_read_b128 v[202:205], v219 offset:55296
	ds_read_b128 v[206:209], v219 offset:56320
	s_add_i32 s1, s1, s4
	v_lshl_add_u64 v[176:177], v[176:177], 0, s[12:13]
	s_mov_b32 m0, s1
	s_nop 0
	global_load_lds_dwordx4 v[176:177], off
	v_lshl_add_u64 v[176:177], v[220:221], 0, s[12:13]
	s_add_i32 m0, s1, 0x2000
	s_nop 0
	global_load_lds_dwordx4 v[176:177], off
	s_mov_b32 m0, s34
	v_lshl_add_u64 v[176:177], v[246:247], 0, s[12:13]
	global_load_lds_dwordx4 v[176:177], off
	v_lshl_add_u64 v[176:177], v[248:249], 0, s[12:13]
	s_mov_b32 m0, s46
	s_nop 0
	global_load_lds_dwordx4 v[176:177], off
	s_add_u32 s22, s30, 0x40080
	s_addc_u32 s23, s31, 0
	s_add_i32 s1, s33, s4
	s_mov_b32 m0, s1
	s_nop 0
	global_load_lds_dwordx4 v0, s[22:23]
	s_add_i32 m0, s1, 0x2000
	s_nop 0
	global_load_lds_dwordx4 v178, s[22:23]
	s_waitcnt vmcnt(8)
	s_waitcnt lgkmcnt(0)
	v_mfma_f32_16x16x32_bf16 v[62:65], v[130:133], v[146:149], v[62:65]
	v_mfma_f32_16x16x32_bf16 v[58:61], v[138:141], v[146:149], v[58:61]
	v_mfma_f32_16x16x32_bf16 v[54:57], v[130:133], v[154:157], v[54:57]
	v_mfma_f32_16x16x32_bf16 v[46:49], v[138:141], v[154:157], v[46:49]
	s_barrier
	s_setprio 1
	v_mfma_f32_16x16x32_bf16 v[38:41], v[130:133], v[194:197], v[38:41]
	v_mfma_f32_16x16x32_bf16 v[30:33], v[138:141], v[194:197], v[30:33]
	v_mfma_f32_16x16x32_bf16 v[22:25], v[130:133], v[202:205], v[22:25]
	v_mfma_f32_16x16x32_bf16 v[14:17], v[138:141], v[202:205], v[14:17]
	v_mfma_f32_16x16x32_bf16 v[62:65], v[134:137], v[150:153], v[62:65]
	v_mfma_f32_16x16x32_bf16 v[58:61], v[142:145], v[150:153], v[58:61]
	v_mfma_f32_16x16x32_bf16 v[54:57], v[134:137], v[158:161], v[54:57]
	v_mfma_f32_16x16x32_bf16 v[46:49], v[142:145], v[158:161], v[46:49]
	v_mfma_f32_16x16x32_bf16 v[38:41], v[134:137], v[198:201], v[38:41]
	v_mfma_f32_16x16x32_bf16 v[30:33], v[142:145], v[198:201], v[30:33]
	v_mfma_f32_16x16x32_bf16 v[22:25], v[134:137], v[206:209], v[22:25]
	v_mfma_f32_16x16x32_bf16 v[14:17], v[142:145], v[206:209], v[14:17]
	v_mfma_f32_16x16x32_bf16 v[50:53], v[230:233], v[146:149], v[50:53]
	v_mfma_f32_16x16x32_bf16 v[42:45], v[238:241], v[146:149], v[42:45]
	v_mfma_f32_16x16x32_bf16 v[34:37], v[230:233], v[154:157], v[34:37]
	v_mfma_f32_16x16x32_bf16 v[26:29], v[238:241], v[154:157], v[26:29]
	v_mfma_f32_16x16x32_bf16 v[18:21], v[230:233], v[194:197], v[18:21]
	v_mfma_f32_16x16x32_bf16 v[10:13], v[238:241], v[194:197], v[10:13]
	v_mfma_f32_16x16x32_bf16 v[6:9], v[230:233], v[202:205], v[6:9]
	v_mfma_f32_16x16x32_bf16 v[2:5], v[238:241], v[202:205], v[2:5]
	v_mfma_f32_16x16x32_bf16 v[50:53], v[234:237], v[150:153], v[50:53]
	v_mfma_f32_16x16x32_bf16 v[42:45], v[242:245], v[150:153], v[42:45]
	v_mfma_f32_16x16x32_bf16 v[34:37], v[234:237], v[158:161], v[34:37]
	v_mfma_f32_16x16x32_bf16 v[26:29], v[242:245], v[158:161], v[26:29]
	v_mfma_f32_16x16x32_bf16 v[18:21], v[234:237], v[198:201], v[18:21]
	v_mfma_f32_16x16x32_bf16 v[10:13], v[242:245], v[198:201], v[10:13]
	v_mfma_f32_16x16x32_bf16 v[6:9], v[234:237], v[206:209], v[6:9]
	v_mfma_f32_16x16x32_bf16 v[2:5], v[242:245], v[206:209], v[2:5]
	s_setprio 0
	s_add_i32 s54, s54, 2
	s_add_u32 s42, s42, 0x100
	s_addc_u32 s43, s43, 0
	s_add_u32 s52, s52, 0x100
	s_addc_u32 s53, s53, 0
	s_cmp_gt_u32 s54, 13
	s_barrier
	s_cbranch_scc0 .LBB0_289
	s_cmpk_gt_u32 s0, 0xff
	s_cbranch_scc1 .Lrs_proj0_post
	s_barrier

.Lrs_proj1_pre:
	s_add_u32 s1, s28, 0xfffc0080
	s_addc_u32 s22, s29, -1
	s_add_i32 s23, 0, 0x10000
	v_add_u32_e32 v158, s23, v181
	ds_read_b128 v[130:133], v158
	ds_read_b128 v[134:137], v158 offset:1024
	ds_read_b128 v[154:157], v158 offset:2048
	ds_read_b128 v[186:189], v158 offset:3072
	s_cmp_eq_u32 s44, 12
	s_cselect_b32 s43, s17, s22
	s_cselect_b32 s42, s20, s1
	s_cselect_b32 s31, s9, s34
	s_cselect_b32 s30, s21, s25
	v_lshl_add_u64 v[160:161], s[28:29], 0, v[150:151]
	s_add_i32 m0, s49, 0xc000
	ds_read_b128 v[190:193], v185
	ds_read_b128 v[194:197], v185 offset:1024
	ds_read_b128 v[198:201], v185 offset:2048
	ds_read_b128 v[202:205], v185 offset:3072
	ds_read_b128 v[206:209], v185 offset:4096
	ds_read_b128 v[216:219], v185 offset:5120
	ds_read_b128 v[230:233], v185 offset:6144
	ds_read_b128 v[234:237], v185 offset:7168
	global_load_lds_dwordx4 v[160:161], off
	v_lshl_add_u64 v[160:161], s[28:29], 0, v[152:153]
	s_add_i32 m0, s49, 0xe000
	s_nop 0
	global_load_lds_dwordx4 v[160:161], off
	s_add_i32 s1, 0, 0x14000
	v_add_u32_e32 v158, s1, v181
	ds_read_b128 v[238:241], v158
	ds_read_b128 v[242:245], v158 offset:1024
	ds_read_b128 v[246:249], v158 offset:2048
	ds_read_b128 v[176:179], v158 offset:3072
	s_waitcnt vmcnt(8)
	s_waitcnt lgkmcnt(0)
	v_mfma_f32_16x16x32_bf16 v[126:129], v[130:133], v[190:193], 0
	v_mfma_f32_16x16x32_bf16 v[122:125], v[154:157], v[190:193], 0
	v_mfma_f32_16x16x32_bf16 v[110:113], v[130:133], v[198:201], 0
	v_mfma_f32_16x16x32_bf16 v[106:109], v[154:157], v[198:201], 0
	s_barrier
	s_setprio 1
	v_mfma_f32_16x16x32_bf16 v[94:97], v[130:133], v[206:209], 0
	v_mfma_f32_16x16x32_bf16 v[90:93], v[154:157], v[206:209], 0
	v_mfma_f32_16x16x32_bf16 v[78:81], v[130:133], v[230:233], 0
	v_mfma_f32_16x16x32_bf16 v[74:77], v[154:157], v[230:233], 0
	v_mfma_f32_16x16x32_bf16 v[126:129], v[134:137], v[194:197], v[126:129]
	v_mfma_f32_16x16x32_bf16 v[122:125], v[186:189], v[194:197], v[122:125]
	v_mfma_f32_16x16x32_bf16 v[110:113], v[134:137], v[202:205], v[110:113]
	v_mfma_f32_16x16x32_bf16 v[106:109], v[186:189], v[202:205], v[106:109]
	v_mfma_f32_16x16x32_bf16 v[94:97], v[134:137], v[216:219], v[94:97]
	v_mfma_f32_16x16x32_bf16 v[90:93], v[186:189], v[216:219], v[90:93]
	v_mfma_f32_16x16x32_bf16 v[78:81], v[134:137], v[234:237], v[78:81]
	v_mfma_f32_16x16x32_bf16 v[74:77], v[186:189], v[234:237], v[74:77]
	v_mfma_f32_16x16x32_bf16 v[118:121], v[238:241], v[190:193], 0
	v_mfma_f32_16x16x32_bf16 v[114:117], v[246:249], v[190:193], 0
	v_mfma_f32_16x16x32_bf16 v[102:105], v[238:241], v[198:201], 0
	v_mfma_f32_16x16x32_bf16 v[98:101], v[246:249], v[198:201], 0
	v_mfma_f32_16x16x32_bf16 v[86:89], v[238:241], v[206:209], 0
	v_mfma_f32_16x16x32_bf16 v[82:85], v[246:249], v[206:209], 0
	v_mfma_f32_16x16x32_bf16 v[70:73], v[238:241], v[230:233], 0
	v_mfma_f32_16x16x32_bf16 v[66:69], v[246:249], v[230:233], 0
	v_mfma_f32_16x16x32_bf16 v[118:121], v[242:245], v[194:197], v[118:121]
	v_mfma_f32_16x16x32_bf16 v[114:117], v[176:179], v[194:197], v[114:117]
	v_mfma_f32_16x16x32_bf16 v[102:105], v[242:245], v[202:205], v[102:105]
	v_mfma_f32_16x16x32_bf16 v[98:101], v[176:179], v[202:205], v[98:101]
	v_mfma_f32_16x16x32_bf16 v[86:89], v[242:245], v[216:219], v[86:89]
	v_mfma_f32_16x16x32_bf16 v[82:85], v[176:179], v[216:219], v[82:85]
	v_mfma_f32_16x16x32_bf16 v[70:73], v[242:245], v[234:237], v[70:73]
	v_mfma_f32_16x16x32_bf16 v[66:69], v[176:179], v[234:237], v[66:69]
	s_setprio 0
	s_barrier
	ds_read_b128 v[190:193], v185 offset:16384
	ds_read_b128 v[194:197], v185 offset:17408
	ds_read_b128 v[198:201], v185 offset:18432
	ds_read_b128 v[202:205], v185 offset:19456
	ds_read_b128 v[206:209], v185 offset:20480
	ds_read_b128 v[216:219], v185 offset:21504
	ds_read_b128 v[230:233], v185 offset:22528
	ds_read_b128 v[234:237], v185 offset:23552
	s_cbranch_vccz .Lss_proj1
	v_lshlrev_b32_e32 v160, 4, v167
	s_lshl_b32 m0, s49, 1
	v_add_u32_e32 v160, s49, v160
	s_add_i32 m0, m0, 0x20000
	s_mov_b64 vcc, 0
	global_load_lds_dwordx4 v160, s[98:99]
	global_load_lds_dwordx4 v160, s[98:99] offset:1024
	s_add_i32 s22, s23, s48
	v_lshl_add_u64 v[160:161], s[30:31], 0, v[0:1]
	s_mov_b32 m0, s22
	s_nop 0
	global_load_lds_dwordx4 v[160:161], off
	v_lshl_add_u64 v[220:221], s[30:31], 0, v[138:139]
	s_add_i32 m0, s22, 0x2000
	s_nop 0
	global_load_lds_dwordx4 v[220:221], off
	s_mov_b32 m0, s49
	v_lshl_add_u64 v[250:251], s[42:43], 0, v[142:143]
	global_load_lds_dwordx4 v[250:251], off
	v_lshl_add_u64 v[168:169], s[42:43], 0, v[140:141]
	s_mov_b32 m0, s50
	s_nop 0
	global_load_lds_dwordx4 v[168:169], off
	s_add_u32 s22, s30, 0x40000
	s_addc_u32 s23, s31, 0
	s_add_i32 s1, s1, s48
	s_mov_b32 m0, s1
	s_nop 0
	global_load_lds_dwordx4 v0, s[22:23]
	s_add_i32 m0, s1, 0x2000
	s_nop 0
	global_load_lds_dwordx4 v138, s[22:23]
	s_waitcnt vmcnt(8)
	s_waitcnt lgkmcnt(0)
	v_mfma_f32_16x16x32_bf16 v[62:65], v[130:133], v[190:193], 0
	v_mfma_f32_16x16x32_bf16 v[58:61], v[154:157], v[190:193], 0
	v_mfma_f32_16x16x32_bf16 v[46:49], v[130:133], v[198:201], 0
	v_mfma_f32_16x16x32_bf16 v[42:45], v[154:157], v[198:201], 0
	s_barrier
	s_setprio 1
	v_mfma_f32_16x16x32_bf16 v[30:33], v[130:133], v[206:209], 0
	v_mfma_f32_16x16x32_bf16 v[26:29], v[154:157], v[206:209], 0
	v_mfma_f32_16x16x32_bf16 v[14:17], v[130:133], v[230:233], 0
	v_mfma_f32_16x16x32_bf16 v[10:13], v[154:157], v[230:233], 0
	v_mfma_f32_16x16x32_bf16 v[62:65], v[134:137], v[194:197], v[62:65]
	v_mfma_f32_16x16x32_bf16 v[58:61], v[186:189], v[194:197], v[58:61]
	v_mfma_f32_16x16x32_bf16 v[46:49], v[134:137], v[202:205], v[46:49]
	v_mfma_f32_16x16x32_bf16 v[42:45], v[186:189], v[202:205], v[42:45]
	v_mfma_f32_16x16x32_bf16 v[30:33], v[134:137], v[216:219], v[30:33]
	v_mfma_f32_16x16x32_bf16 v[26:29], v[186:189], v[216:219], v[26:29]
	v_mfma_f32_16x16x32_bf16 v[14:17], v[134:137], v[234:237], v[14:17]
	v_mfma_f32_16x16x32_bf16 v[10:13], v[186:189], v[234:237], v[10:13]
	v_mfma_f32_16x16x32_bf16 v[54:57], v[238:241], v[190:193], 0
	v_mfma_f32_16x16x32_bf16 v[50:53], v[246:249], v[190:193], 0
	v_mfma_f32_16x16x32_bf16 v[38:41], v[238:241], v[198:201], 0
	v_mfma_f32_16x16x32_bf16 v[34:37], v[246:249], v[198:201], 0
	v_mfma_f32_16x16x32_bf16 v[22:25], v[238:241], v[206:209], 0
	v_mfma_f32_16x16x32_bf16 v[18:21], v[246:249], v[206:209], 0
	v_mfma_f32_16x16x32_bf16 v[6:9], v[238:241], v[230:233], 0
	v_mfma_f32_16x16x32_bf16 v[2:5], v[246:249], v[230:233], 0
	v_mfma_f32_16x16x32_bf16 v[54:57], v[242:245], v[194:197], v[54:57]
	v_mfma_f32_16x16x32_bf16 v[50:53], v[176:179], v[194:197], v[50:53]
	v_mfma_f32_16x16x32_bf16 v[38:41], v[242:245], v[202:205], v[38:41]
	v_mfma_f32_16x16x32_bf16 v[34:37], v[176:179], v[202:205], v[34:37]
	v_mfma_f32_16x16x32_bf16 v[22:25], v[242:245], v[216:219], v[22:25]
	v_mfma_f32_16x16x32_bf16 v[18:21], v[176:179], v[216:219], v[18:21]
	v_mfma_f32_16x16x32_bf16 v[6:9], v[242:245], v[234:237], v[6:9]
	v_mfma_f32_16x16x32_bf16 v[2:5], v[176:179], v[234:237], v[2:5]
	s_setprio 0
	s_barrier
	s_add_i32 s1, 0, 0x18000
	v_add_u32_e32 v158, s1, v181
	ds_read_b128 v[130:133], v158
	ds_read_b128 v[134:137], v158 offset:1024
	ds_read_b128 v[154:157], v158 offset:2048
	ds_read_b128 v[176:179], v158 offset:3072
	s_add_u32 s22, s42, 0x40000
	s_addc_u32 s23, s43, 0
	s_mov_b32 m0, s51
	v_lshl_add_u64 v[234:235], s[22:23], 0, v[142:143]
	ds_read_b128 v[186:189], v185 offset:32768
	ds_read_b128 v[190:193], v185 offset:33792
	ds_read_b128 v[194:197], v185 offset:34816
	ds_read_b128 v[198:201], v185 offset:35840
	ds_read_b128 v[202:205], v185 offset:36864
	ds_read_b128 v[206:209], v185 offset:37888
	ds_read_b128 v[216:219], v185 offset:38912
	ds_read_b128 v[230:233], v185 offset:39936
	global_load_lds_dwordx4 v[234:235], off
	v_lshl_add_u64 v[234:235], s[22:23], 0, v[140:141]
	s_mov_b32 m0, s52
	s_nop 0
	global_load_lds_dwordx4 v[234:235], off
	s_add_i32 s33, 0, 0x1c000
	v_add_u32_e32 v158, s33, v181
	ds_read_b128 v[234:237], v158
	ds_read_b128 v[238:241], v158 offset:1024
	ds_read_b128 v[242:245], v158 offset:2048
	ds_read_b128 v[246:249], v158 offset:3072
	s_waitcnt vmcnt(8)
	s_waitcnt lgkmcnt(0)
	v_mfma_f32_16x16x32_bf16 v[126:129], v[130:133], v[186:189], v[126:129]
	v_mfma_f32_16x16x32_bf16 v[122:125], v[154:157], v[186:189], v[122:125]
	v_mfma_f32_16x16x32_bf16 v[110:113], v[130:133], v[194:197], v[110:113]
	v_mfma_f32_16x16x32_bf16 v[106:109], v[154:157], v[194:197], v[106:109]
	s_barrier
	s_setprio 1
	v_mfma_f32_16x16x32_bf16 v[94:97], v[130:133], v[202:205], v[94:97]
	v_mfma_f32_16x16x32_bf16 v[90:93], v[154:157], v[202:205], v[90:93]
	v_mfma_f32_16x16x32_bf16 v[78:81], v[130:133], v[216:219], v[78:81]
	v_mfma_f32_16x16x32_bf16 v[74:77], v[154:157], v[216:219], v[74:77]
	v_mfma_f32_16x16x32_bf16 v[126:129], v[134:137], v[190:193], v[126:129]
	v_mfma_f32_16x16x32_bf16 v[122:125], v[176:179], v[190:193], v[122:125]
	v_mfma_f32_16x16x32_bf16 v[110:113], v[134:137], v[198:201], v[110:113]
	v_mfma_f32_16x16x32_bf16 v[106:109], v[176:179], v[198:201], v[106:109]
	v_mfma_f32_16x16x32_bf16 v[94:97], v[134:137], v[206:209], v[94:97]
	v_mfma_f32_16x16x32_bf16 v[90:93], v[176:179], v[206:209], v[90:93]
	v_mfma_f32_16x16x32_bf16 v[78:81], v[134:137], v[230:233], v[78:81]
	v_mfma_f32_16x16x32_bf16 v[74:77], v[176:179], v[230:233], v[74:77]
	v_mfma_f32_16x16x32_bf16 v[118:121], v[234:237], v[186:189], v[118:121]
	v_mfma_f32_16x16x32_bf16 v[114:117], v[242:245], v[186:189], v[114:117]
	v_mfma_f32_16x16x32_bf16 v[102:105], v[234:237], v[194:197], v[102:105]
	v_mfma_f32_16x16x32_bf16 v[98:101], v[242:245], v[194:197], v[98:101]
	v_mfma_f32_16x16x32_bf16 v[86:89], v[234:237], v[202:205], v[86:89]
	v_mfma_f32_16x16x32_bf16 v[82:85], v[242:245], v[202:205], v[82:85]
	v_mfma_f32_16x16x32_bf16 v[70:73], v[234:237], v[216:219], v[70:73]
	v_mfma_f32_16x16x32_bf16 v[66:69], v[242:245], v[216:219], v[66:69]
	v_mfma_f32_16x16x32_bf16 v[118:121], v[238:241], v[190:193], v[118:121]
	v_mfma_f32_16x16x32_bf16 v[114:117], v[246:249], v[190:193], v[114:117]
	v_mfma_f32_16x16x32_bf16 v[102:105], v[238:241], v[198:201], v[102:105]
	v_mfma_f32_16x16x32_bf16 v[98:101], v[246:249], v[198:201], v[98:101]
	v_mfma_f32_16x16x32_bf16 v[86:89], v[238:241], v[206:209], v[86:89]
	v_mfma_f32_16x16x32_bf16 v[82:85], v[246:249], v[206:209], v[82:85]
	v_mfma_f32_16x16x32_bf16 v[70:73], v[238:241], v[230:233], v[70:73]
	v_mfma_f32_16x16x32_bf16 v[66:69], v[246:249], v[230:233], v[66:69]
	s_setprio 0
	s_barrier
	ds_read_b128 v[186:189], v185 offset:49152
	ds_read_b128 v[190:193], v185 offset:50176
	ds_read_b128 v[194:197], v185 offset:51200
	ds_read_b128 v[198:201], v185 offset:52224
	ds_read_b128 v[202:205], v185 offset:53248
	ds_read_b128 v[206:209], v185 offset:54272
	ds_read_b128 v[216:219], v185 offset:55296
	ds_read_b128 v[230:233], v185 offset:56320
	s_add_i32 s1, s1, s48
	v_lshl_add_u64 v[160:161], v[160:161], 0, s[12:13]
	s_mov_b32 m0, s1
	s_nop 0
	global_load_lds_dwordx4 v[160:161], off
	v_lshl_add_u64 v[160:161], v[220:221], 0, s[12:13]
	s_add_i32 m0, s1, 0x2000
	s_nop 0
	global_load_lds_dwordx4 v[160:161], off
	s_mov_b32 m0, s55
	v_lshl_add_u64 v[160:161], v[250:251], 0, s[12:13]
	global_load_lds_dwordx4 v[160:161], off
	v_lshl_add_u64 v[160:161], v[168:169], 0, s[12:13]
	s_mov_b32 m0, s56
	s_nop 0
	global_load_lds_dwordx4 v[160:161], off
	s_add_u32 s22, s30, 0x40080
	s_addc_u32 s23, s31, 0
	s_add_i32 s1, s33, s48
	s_mov_b32 m0, s1
	s_nop 0
	global_load_lds_dwordx4 v0, s[22:23]
	s_add_i32 m0, s1, 0x2000
	s_nop 0
	global_load_lds_dwordx4 v138, s[22:23]
	s_waitcnt vmcnt(8)
	s_waitcnt lgkmcnt(0)
	v_mfma_f32_16x16x32_bf16 v[62:65], v[130:133], v[186:189], v[62:65]
	v_mfma_f32_16x16x32_bf16 v[58:61], v[154:157], v[186:189], v[58:61]
	v_mfma_f32_16x16x32_bf16 v[46:49], v[130:133], v[194:197], v[46:49]
	v_mfma_f32_16x16x32_bf16 v[42:45], v[154:157], v[194:197], v[42:45]
	s_barrier
	s_setprio 1
	v_mfma_f32_16x16x32_bf16 v[30:33], v[130:133], v[202:205], v[30:33]
	v_mfma_f32_16x16x32_bf16 v[26:29], v[154:157], v[202:205], v[26:29]
	v_mfma_f32_16x16x32_bf16 v[14:17], v[130:133], v[216:219], v[14:17]
	v_mfma_f32_16x16x32_bf16 v[10:13], v[154:157], v[216:219], v[10:13]
	v_mfma_f32_16x16x32_bf16 v[62:65], v[134:137], v[190:193], v[62:65]
	v_mfma_f32_16x16x32_bf16 v[58:61], v[176:179], v[190:193], v[58:61]
	v_mfma_f32_16x16x32_bf16 v[46:49], v[134:137], v[198:201], v[46:49]
	v_mfma_f32_16x16x32_bf16 v[42:45], v[176:179], v[198:201], v[42:45]
	v_mfma_f32_16x16x32_bf16 v[30:33], v[134:137], v[206:209], v[30:33]
	v_mfma_f32_16x16x32_bf16 v[26:29], v[176:179], v[206:209], v[26:29]
	v_mfma_f32_16x16x32_bf16 v[14:17], v[134:137], v[230:233], v[14:17]
	v_mfma_f32_16x16x32_bf16 v[10:13], v[176:179], v[230:233], v[10:13]
	v_mfma_f32_16x16x32_bf16 v[54:57], v[234:237], v[186:189], v[54:57]
	v_mfma_f32_16x16x32_bf16 v[50:53], v[242:245], v[186:189], v[50:53]
	v_mfma_f32_16x16x32_bf16 v[38:41], v[234:237], v[194:197], v[38:41]
	v_mfma_f32_16x16x32_bf16 v[34:37], v[242:245], v[194:197], v[34:37]
	v_mfma_f32_16x16x32_bf16 v[22:25], v[234:237], v[202:205], v[22:25]
	v_mfma_f32_16x16x32_bf16 v[18:21], v[242:245], v[202:205], v[18:21]
	v_mfma_f32_16x16x32_bf16 v[6:9], v[234:237], v[216:219], v[6:9]
	v_mfma_f32_16x16x32_bf16 v[2:5], v[242:245], v[216:219], v[2:5]
	v_mfma_f32_16x16x32_bf16 v[54:57], v[238:241], v[190:193], v[54:57]
	v_mfma_f32_16x16x32_bf16 v[50:53], v[246:249], v[190:193], v[50:53]
	v_mfma_f32_16x16x32_bf16 v[38:41], v[238:241], v[198:201], v[38:41]
	v_mfma_f32_16x16x32_bf16 v[34:37], v[246:249], v[198:201], v[34:37]
	v_mfma_f32_16x16x32_bf16 v[22:25], v[238:241], v[206:209], v[22:25]
	v_mfma_f32_16x16x32_bf16 v[18:21], v[246:249], v[206:209], v[18:21]
	v_mfma_f32_16x16x32_bf16 v[6:9], v[238:241], v[230:233], v[6:9]
	v_mfma_f32_16x16x32_bf16 v[2:5], v[246:249], v[230:233], v[2:5]
	s_setprio 0
	s_add_i32 s44, s44, 2
	s_add_u32 s28, s28, 0x100
	s_addc_u32 s29, s29, 0
	s_add_u32 s25, s25, 0x100
	s_addc_u32 s34, s34, 0
	s_cmp_gt_u32 s44, 13
	s_barrier
.LBB0_362:
	s_add_u32 s1, s28, 0xfffc0080
	s_addc_u32 s22, s29, -1
	s_add_i32 s23, 0, 0x10000
	v_add_u32_e32 v158, s23, v181
	ds_read_b128 v[130:133], v158
	ds_read_b128 v[134:137], v158 offset:1024
	ds_read_b128 v[154:157], v158 offset:2048
	ds_read_b128 v[186:189], v158 offset:3072
	s_cmp_eq_u32 s44, 12
	s_cselect_b32 s43, s17, s22
	s_cselect_b32 s42, s20, s1
	s_cselect_b32 s31, s9, s34
	s_cselect_b32 s30, s21, s25
	v_lshl_add_u64 v[160:161], s[28:29], 0, v[150:151]
	s_add_i32 m0, s49, 0xc000
	ds_read_b128 v[190:193], v185
	ds_read_b128 v[194:197], v185 offset:1024
	ds_read_b128 v[198:201], v185 offset:2048
	ds_read_b128 v[202:205], v185 offset:3072
	ds_read_b128 v[206:209], v185 offset:4096
	ds_read_b128 v[216:219], v185 offset:5120
	ds_read_b128 v[230:233], v185 offset:6144
	ds_read_b128 v[234:237], v185 offset:7168
	global_load_lds_dwordx4 v[160:161], off
	v_lshl_add_u64 v[160:161], s[28:29], 0, v[152:153]
	s_add_i32 m0, s49, 0xe000
	s_nop 0
	global_load_lds_dwordx4 v[160:161], off
	s_add_i32 s1, 0, 0x14000
	v_add_u32_e32 v158, s1, v181
	ds_read_b128 v[238:241], v158
	ds_read_b128 v[242:245], v158 offset:1024
	ds_read_b128 v[246:249], v158 offset:2048
	ds_read_b128 v[176:179], v158 offset:3072
	s_waitcnt vmcnt(8)
	s_waitcnt lgkmcnt(0)
	v_mfma_f32_16x16x32_bf16 v[126:129], v[130:133], v[190:193], v[126:129]
	v_mfma_f32_16x16x32_bf16 v[122:125], v[154:157], v[190:193], v[122:125]
	v_mfma_f32_16x16x32_bf16 v[110:113], v[130:133], v[198:201], v[110:113]
	v_mfma_f32_16x16x32_bf16 v[106:109], v[154:157], v[198:201], v[106:109]
	s_barrier
	s_setprio 1
	v_mfma_f32_16x16x32_bf16 v[94:97], v[130:133], v[206:209], v[94:97]
	v_mfma_f32_16x16x32_bf16 v[90:93], v[154:157], v[206:209], v[90:93]
	v_mfma_f32_16x16x32_bf16 v[78:81], v[130:133], v[230:233], v[78:81]
	v_mfma_f32_16x16x32_bf16 v[74:77], v[154:157], v[230:233], v[74:77]
	v_mfma_f32_16x16x32_bf16 v[126:129], v[134:137], v[194:197], v[126:129]
	v_mfma_f32_16x16x32_bf16 v[122:125], v[186:189], v[194:197], v[122:125]
	v_mfma_f32_16x16x32_bf16 v[110:113], v[134:137], v[202:205], v[110:113]
	v_mfma_f32_16x16x32_bf16 v[106:109], v[186:189], v[202:205], v[106:109]
	v_mfma_f32_16x16x32_bf16 v[94:97], v[134:137], v[216:219], v[94:97]
	v_mfma_f32_16x16x32_bf16 v[90:93], v[186:189], v[216:219], v[90:93]
	v_mfma_f32_16x16x32_bf16 v[78:81], v[134:137], v[234:237], v[78:81]
	v_mfma_f32_16x16x32_bf16 v[74:77], v[186:189], v[234:237], v[74:77]
	v_mfma_f32_16x16x32_bf16 v[118:121], v[238:241], v[190:193], v[118:121]
	v_mfma_f32_16x16x32_bf16 v[114:117], v[246:249], v[190:193], v[114:117]
	v_mfma_f32_16x16x32_bf16 v[102:105], v[238:241], v[198:201], v[102:105]
	v_mfma_f32_16x16x32_bf16 v[98:101], v[246:249], v[198:201], v[98:101]
	v_mfma_f32_16x16x32_bf16 v[86:89], v[238:241], v[206:209], v[86:89]
	v_mfma_f32_16x16x32_bf16 v[82:85], v[246:249], v[206:209], v[82:85]
	v_mfma_f32_16x16x32_bf16 v[70:73], v[238:241], v[230:233], v[70:73]
	v_mfma_f32_16x16x32_bf16 v[66:69], v[246:249], v[230:233], v[66:69]
	v_mfma_f32_16x16x32_bf16 v[118:121], v[242:245], v[194:197], v[118:121]
	v_mfma_f32_16x16x32_bf16 v[114:117], v[176:179], v[194:197], v[114:117]
	v_mfma_f32_16x16x32_bf16 v[102:105], v[242:245], v[202:205], v[102:105]
	v_mfma_f32_16x16x32_bf16 v[98:101], v[176:179], v[202:205], v[98:101]
	v_mfma_f32_16x16x32_bf16 v[86:89], v[242:245], v[216:219], v[86:89]
	v_mfma_f32_16x16x32_bf16 v[82:85], v[176:179], v[216:219], v[82:85]
	v_mfma_f32_16x16x32_bf16 v[70:73], v[242:245], v[234:237], v[70:73]
	v_mfma_f32_16x16x32_bf16 v[66:69], v[176:179], v[234:237], v[66:69]
	s_setprio 0
	s_barrier
	ds_read_b128 v[190:193], v185 offset:16384
	ds_read_b128 v[194:197], v185 offset:17408
	ds_read_b128 v[198:201], v185 offset:18432
	ds_read_b128 v[202:205], v185 offset:19456
	ds_read_b128 v[206:209], v185 offset:20480
	ds_read_b128 v[216:219], v185 offset:21504
	ds_read_b128 v[230:233], v185 offset:22528
	ds_read_b128 v[234:237], v185 offset:23552
	s_cbranch_vccz .Lss_proj1
	v_lshlrev_b32_e32 v160, 4, v167
	s_lshl_b32 m0, s49, 1
	v_add_u32_e32 v160, s49, v160
	s_add_i32 m0, m0, 0x20000
	s_mov_b64 vcc, 0
	global_load_lds_dwordx4 v160, s[98:99]
	global_load_lds_dwordx4 v160, s[98:99] offset:1024
.Lss_proj1:
	s_add_i32 s22, s23, s48
	v_lshl_add_u64 v[160:161], s[30:31], 0, v[0:1]
	s_mov_b32 m0, s22
	s_nop 0
	global_load_lds_dwordx4 v[160:161], off
	v_lshl_add_u64 v[220:221], s[30:31], 0, v[138:139]
	s_add_i32 m0, s22, 0x2000
	s_nop 0
	global_load_lds_dwordx4 v[220:221], off
	s_mov_b32 m0, s49
	v_lshl_add_u64 v[250:251], s[42:43], 0, v[142:143]
	global_load_lds_dwordx4 v[250:251], off
	v_lshl_add_u64 v[168:169], s[42:43], 0, v[140:141]
	s_mov_b32 m0, s50
	s_nop 0
	global_load_lds_dwordx4 v[168:169], off
	s_add_u32 s22, s30, 0x40000
	s_addc_u32 s23, s31, 0
	s_add_i32 s1, s1, s48
	s_mov_b32 m0, s1
	s_nop 0
	global_load_lds_dwordx4 v0, s[22:23]
	s_add_i32 m0, s1, 0x2000
	s_nop 0
	global_load_lds_dwordx4 v138, s[22:23]
	s_waitcnt vmcnt(8)
	s_waitcnt lgkmcnt(0)
	v_mfma_f32_16x16x32_bf16 v[62:65], v[130:133], v[190:193], v[62:65]
	v_mfma_f32_16x16x32_bf16 v[58:61], v[154:157], v[190:193], v[58:61]
	v_mfma_f32_16x16x32_bf16 v[46:49], v[130:133], v[198:201], v[46:49]
	v_mfma_f32_16x16x32_bf16 v[42:45], v[154:157], v[198:201], v[42:45]
	s_barrier
	s_setprio 1
	v_mfma_f32_16x16x32_bf16 v[30:33], v[130:133], v[206:209], v[30:33]
	v_mfma_f32_16x16x32_bf16 v[26:29], v[154:157], v[206:209], v[26:29]
	v_mfma_f32_16x16x32_bf16 v[14:17], v[130:133], v[230:233], v[14:17]
	v_mfma_f32_16x16x32_bf16 v[10:13], v[154:157], v[230:233], v[10:13]
	v_mfma_f32_16x16x32_bf16 v[62:65], v[134:137], v[194:197], v[62:65]
	v_mfma_f32_16x16x32_bf16 v[58:61], v[186:189], v[194:197], v[58:61]
	v_mfma_f32_16x16x32_bf16 v[46:49], v[134:137], v[202:205], v[46:49]
	v_mfma_f32_16x16x32_bf16 v[42:45], v[186:189], v[202:205], v[42:45]
	v_mfma_f32_16x16x32_bf16 v[30:33], v[134:137], v[216:219], v[30:33]
	v_mfma_f32_16x16x32_bf16 v[26:29], v[186:189], v[216:219], v[26:29]
	v_mfma_f32_16x16x32_bf16 v[14:17], v[134:137], v[234:237], v[14:17]
	v_mfma_f32_16x16x32_bf16 v[10:13], v[186:189], v[234:237], v[10:13]
	v_mfma_f32_16x16x32_bf16 v[54:57], v[238:241], v[190:193], v[54:57]
	v_mfma_f32_16x16x32_bf16 v[50:53], v[246:249], v[190:193], v[50:53]
	v_mfma_f32_16x16x32_bf16 v[38:41], v[238:241], v[198:201], v[38:41]
	v_mfma_f32_16x16x32_bf16 v[34:37], v[246:249], v[198:201], v[34:37]
	v_mfma_f32_16x16x32_bf16 v[22:25], v[238:241], v[206:209], v[22:25]
	v_mfma_f32_16x16x32_bf16 v[18:21], v[246:249], v[206:209], v[18:21]
	v_mfma_f32_16x16x32_bf16 v[6:9], v[238:241], v[230:233], v[6:9]
	v_mfma_f32_16x16x32_bf16 v[2:5], v[246:249], v[230:233], v[2:5]
	v_mfma_f32_16x16x32_bf16 v[54:57], v[242:245], v[194:197], v[54:57]
	v_mfma_f32_16x16x32_bf16 v[50:53], v[176:179], v[194:197], v[50:53]
	v_mfma_f32_16x16x32_bf16 v[38:41], v[242:245], v[202:205], v[38:41]
	v_mfma_f32_16x16x32_bf16 v[34:37], v[176:179], v[202:205], v[34:37]
	v_mfma_f32_16x16x32_bf16 v[22:25], v[242:245], v[216:219], v[22:25]
	v_mfma_f32_16x16x32_bf16 v[18:21], v[176:179], v[216:219], v[18:21]
	v_mfma_f32_16x16x32_bf16 v[6:9], v[242:245], v[234:237], v[6:9]
	v_mfma_f32_16x16x32_bf16 v[2:5], v[176:179], v[234:237], v[2:5]
	s_setprio 0
	s_barrier
	s_add_i32 s1, 0, 0x18000
	v_add_u32_e32 v158, s1, v181
	ds_read_b128 v[130:133], v158
	ds_read_b128 v[134:137], v158 offset:1024
	ds_read_b128 v[154:157], v158 offset:2048
	ds_read_b128 v[176:179], v158 offset:3072
	s_add_u32 s22, s42, 0x40000
	s_addc_u32 s23, s43, 0
	s_mov_b32 m0, s51
	v_lshl_add_u64 v[234:235], s[22:23], 0, v[142:143]
	ds_read_b128 v[186:189], v185 offset:32768
	ds_read_b128 v[190:193], v185 offset:33792
	ds_read_b128 v[194:197], v185 offset:34816
	ds_read_b128 v[198:201], v185 offset:35840
	ds_read_b128 v[202:205], v185 offset:36864
	ds_read_b128 v[206:209], v185 offset:37888
	ds_read_b128 v[216:219], v185 offset:38912
	ds_read_b128 v[230:233], v185 offset:39936
	global_load_lds_dwordx4 v[234:235], off
	v_lshl_add_u64 v[234:235], s[22:23], 0, v[140:141]
	s_mov_b32 m0, s52
	s_nop 0
	global_load_lds_dwordx4 v[234:235], off
	s_add_i32 s33, 0, 0x1c000
	v_add_u32_e32 v158, s33, v181
	ds_read_b128 v[234:237], v158
	ds_read_b128 v[238:241], v158 offset:1024
	ds_read_b128 v[242:245], v158 offset:2048
	ds_read_b128 v[246:249], v158 offset:3072
	s_waitcnt vmcnt(8)
	s_waitcnt lgkmcnt(0)
	v_mfma_f32_16x16x32_bf16 v[126:129], v[130:133], v[186:189], v[126:129]
	v_mfma_f32_16x16x32_bf16 v[122:125], v[154:157], v[186:189], v[122:125]
	v_mfma_f32_16x16x32_bf16 v[110:113], v[130:133], v[194:197], v[110:113]
	v_mfma_f32_16x16x32_bf16 v[106:109], v[154:157], v[194:197], v[106:109]
	s_barrier
	s_setprio 1
	v_mfma_f32_16x16x32_bf16 v[94:97], v[130:133], v[202:205], v[94:97]
	v_mfma_f32_16x16x32_bf16 v[90:93], v[154:157], v[202:205], v[90:93]
	v_mfma_f32_16x16x32_bf16 v[78:81], v[130:133], v[216:219], v[78:81]
	v_mfma_f32_16x16x32_bf16 v[74:77], v[154:157], v[216:219], v[74:77]
	v_mfma_f32_16x16x32_bf16 v[126:129], v[134:137], v[190:193], v[126:129]
	v_mfma_f32_16x16x32_bf16 v[122:125], v[176:179], v[190:193], v[122:125]
	v_mfma_f32_16x16x32_bf16 v[110:113], v[134:137], v[198:201], v[110:113]
	v_mfma_f32_16x16x32_bf16 v[106:109], v[176:179], v[198:201], v[106:109]
	v_mfma_f32_16x16x32_bf16 v[94:97], v[134:137], v[206:209], v[94:97]
	v_mfma_f32_16x16x32_bf16 v[90:93], v[176:179], v[206:209], v[90:93]
	v_mfma_f32_16x16x32_bf16 v[78:81], v[134:137], v[230:233], v[78:81]
	v_mfma_f32_16x16x32_bf16 v[74:77], v[176:179], v[230:233], v[74:77]
	v_mfma_f32_16x16x32_bf16 v[118:121], v[234:237], v[186:189], v[118:121]
	v_mfma_f32_16x16x32_bf16 v[114:117], v[242:245], v[186:189], v[114:117]
	v_mfma_f32_16x16x32_bf16 v[102:105], v[234:237], v[194:197], v[102:105]
	v_mfma_f32_16x16x32_bf16 v[98:101], v[242:245], v[194:197], v[98:101]
	v_mfma_f32_16x16x32_bf16 v[86:89], v[234:237], v[202:205], v[86:89]
	v_mfma_f32_16x16x32_bf16 v[82:85], v[242:245], v[202:205], v[82:85]
	v_mfma_f32_16x16x32_bf16 v[70:73], v[234:237], v[216:219], v[70:73]
	v_mfma_f32_16x16x32_bf16 v[66:69], v[242:245], v[216:219], v[66:69]
	v_mfma_f32_16x16x32_bf16 v[118:121], v[238:241], v[190:193], v[118:121]
	v_mfma_f32_16x16x32_bf16 v[114:117], v[246:249], v[190:193], v[114:117]
	v_mfma_f32_16x16x32_bf16 v[102:105], v[238:241], v[198:201], v[102:105]
	v_mfma_f32_16x16x32_bf16 v[98:101], v[246:249], v[198:201], v[98:101]
	v_mfma_f32_16x16x32_bf16 v[86:89], v[238:241], v[206:209], v[86:89]
	v_mfma_f32_16x16x32_bf16 v[82:85], v[246:249], v[206:209], v[82:85]
	v_mfma_f32_16x16x32_bf16 v[70:73], v[238:241], v[230:233], v[70:73]
	v_mfma_f32_16x16x32_bf16 v[66:69], v[246:249], v[230:233], v[66:69]
	s_setprio 0
	s_barrier
	ds_read_b128 v[186:189], v185 offset:49152
	ds_read_b128 v[190:193], v185 offset:50176
	ds_read_b128 v[194:197], v185 offset:51200
	ds_read_b128 v[198:201], v185 offset:52224
	ds_read_b128 v[202:205], v185 offset:53248
	ds_read_b128 v[206:209], v185 offset:54272
	ds_read_b128 v[216:219], v185 offset:55296
	ds_read_b128 v[230:233], v185 offset:56320
	s_add_i32 s1, s1, s48
	v_lshl_add_u64 v[160:161], v[160:161], 0, s[12:13]
	s_mov_b32 m0, s1
	s_nop 0
	global_load_lds_dwordx4 v[160:161], off
	v_lshl_add_u64 v[160:161], v[220:221], 0, s[12:13]
	s_add_i32 m0, s1, 0x2000
	s_nop 0
	global_load_lds_dwordx4 v[160:161], off
	s_mov_b32 m0, s55
	v_lshl_add_u64 v[160:161], v[250:251], 0, s[12:13]
	global_load_lds_dwordx4 v[160:161], off
	v_lshl_add_u64 v[160:161], v[168:169], 0, s[12:13]
	s_mov_b32 m0, s56
	s_nop 0
	global_load_lds_dwordx4 v[160:161], off
	s_add_u32 s22, s30, 0x40080
	s_addc_u32 s23, s31, 0
	s_add_i32 s1, s33, s48
	s_mov_b32 m0, s1
	s_nop 0
	global_load_lds_dwordx4 v0, s[22:23]
	s_add_i32 m0, s1, 0x2000
	s_nop 0
	global_load_lds_dwordx4 v138, s[22:23]
	s_waitcnt vmcnt(8)
	s_waitcnt lgkmcnt(0)
	v_mfma_f32_16x16x32_bf16 v[62:65], v[130:133], v[186:189], v[62:65]
	v_mfma_f32_16x16x32_bf16 v[58:61], v[154:157], v[186:189], v[58:61]
	v_mfma_f32_16x16x32_bf16 v[46:49], v[130:133], v[194:197], v[46:49]
	v_mfma_f32_16x16x32_bf16 v[42:45], v[154:157], v[194:197], v[42:45]
	s_barrier
	s_setprio 1
	v_mfma_f32_16x16x32_bf16 v[30:33], v[130:133], v[202:205], v[30:33]
	v_mfma_f32_16x16x32_bf16 v[26:29], v[154:157], v[202:205], v[26:29]
	v_mfma_f32_16x16x32_bf16 v[14:17], v[130:133], v[216:219], v[14:17]
	v_mfma_f32_16x16x32_bf16 v[10:13], v[154:157], v[216:219], v[10:13]
	v_mfma_f32_16x16x32_bf16 v[62:65], v[134:137], v[190:193], v[62:65]
	v_mfma_f32_16x16x32_bf16 v[58:61], v[176:179], v[190:193], v[58:61]
	v_mfma_f32_16x16x32_bf16 v[46:49], v[134:137], v[198:201], v[46:49]
	v_mfma_f32_16x16x32_bf16 v[42:45], v[176:179], v[198:201], v[42:45]
	v_mfma_f32_16x16x32_bf16 v[30:33], v[134:137], v[206:209], v[30:33]
	v_mfma_f32_16x16x32_bf16 v[26:29], v[176:179], v[206:209], v[26:29]
	v_mfma_f32_16x16x32_bf16 v[14:17], v[134:137], v[230:233], v[14:17]
	v_mfma_f32_16x16x32_bf16 v[10:13], v[176:179], v[230:233], v[10:13]
	v_mfma_f32_16x16x32_bf16 v[54:57], v[234:237], v[186:189], v[54:57]
	v_mfma_f32_16x16x32_bf16 v[50:53], v[242:245], v[186:189], v[50:53]
	v_mfma_f32_16x16x32_bf16 v[38:41], v[234:237], v[194:197], v[38:41]
	v_mfma_f32_16x16x32_bf16 v[34:37], v[242:245], v[194:197], v[34:37]
	v_mfma_f32_16x16x32_bf16 v[22:25], v[234:237], v[202:205], v[22:25]
	v_mfma_f32_16x16x32_bf16 v[18:21], v[242:245], v[202:205], v[18:21]
	v_mfma_f32_16x16x32_bf16 v[6:9], v[234:237], v[216:219], v[6:9]
	v_mfma_f32_16x16x32_bf16 v[2:5], v[242:245], v[216:219], v[2:5]
	v_mfma_f32_16x16x32_bf16 v[54:57], v[238:241], v[190:193], v[54:57]
	v_mfma_f32_16x16x32_bf16 v[50:53], v[246:249], v[190:193], v[50:53]
	v_mfma_f32_16x16x32_bf16 v[38:41], v[238:241], v[198:201], v[38:41]
	v_mfma_f32_16x16x32_bf16 v[34:37], v[246:249], v[198:201], v[34:37]
	v_mfma_f32_16x16x32_bf16 v[22:25], v[238:241], v[206:209], v[22:25]
	v_mfma_f32_16x16x32_bf16 v[18:21], v[246:249], v[206:209], v[18:21]
	v_mfma_f32_16x16x32_bf16 v[6:9], v[238:241], v[230:233], v[6:9]
	v_mfma_f32_16x16x32_bf16 v[2:5], v[246:249], v[230:233], v[2:5]
	s_setprio 0
	s_add_i32 s44, s44, 2
	s_add_u32 s28, s28, 0x100
	s_addc_u32 s29, s29, 0
	s_add_u32 s25, s25, 0x100
	s_addc_u32 s34, s34, 0
	s_cmp_gt_u32 s44, 13
	s_barrier
	s_cbranch_scc0 .LBB0_362
	s_cmpk_gt_u32 s4, 0xff
	s_cbranch_scc1 .Lrs_proj1_post
	s_barrier
